# v54 + next-unit decode/pointer block moved from the unit-loop header to the end of the peeled first K iteration (P1, P3, P6, P7): ~45 scalar instructions off the epilogue-to-first-MFMA path per unit
# baseline (speedup 1.0000x reference)
; #define PG8_STAGE(bufoff, gbase, voff) do { _Pragma("unroll") for (int _i = 0; _i < 2; ++_i) \
;         __builtin_amdgcn_global_load_lds((const unsigned*)((const char*)(gbase) + (voff)[_i]), (PG8_LAS unsigned*)(lds + (bufoff) + ldsw + _i * 8192), 16, 0, 0); } while (0)
; #define PG8_LDA(dst, b, h) do { _Pragma("unroll") for (int m = 0; m < 4; ++m) _Pragma("unroll") for (int k = 0; k < 2; ++k) dst[m][k] = *(const PG8_LAS bf16x8*)(lds + PG8_SA(b, h) + aoff + m * 2048 + k * 1024); } while (0)
; #define PG8_LDB(dst, b, h) do { _Pragma("unroll") for (int n = 0; n < 2; ++n) _Pragma("unroll") for (int k = 0; k < 2; ++k) dst[n][k] = *(const PG8_LAS bf16x8*)(lds + PG8_SB(b, h) + boff + n * 2048 + k * 1024); } while (0)
; #define PG8_MMA(ai, bj, At, Bt) do { __builtin_amdgcn_s_setprio(1); _Pragma("unroll") for (int m = 0; m < 4; ++m) _Pragma("unroll") for (int n = 0; n < 2; ++n) _Pragma("unroll") for (int k = 0; k < 2; ++k) \
;         acc[ai][bj][m][n] = __builtin_amdgcn_mfma_f32_16x16x32_bf16(Bt[n][k], At[m][k], acc[ai][bj][m][n], 0, 0, 0); __builtin_amdgcn_s_setprio(0); } while (0)
; #define PG8_WAIT_V(n) asm volatile("s_waitcnt vmcnt(" #n ")" ::: "memory")
; #define PG8_WAIT_L(n) asm volatile("s_waitcnt lgkmcnt(" #n ")" ::: "memory")
; #define PG8_BAR __builtin_amdgcn_s_barrier()
; #define PG8_SCHED __builtin_amdgcn_sched_barrier(0)
; template <class Epi, class Sched, bool ALIGN_EPI = false, bool SP2 = false>
; __device__ __forceinline__ void gemm_phase(PG8_LAS unsigned char* lds, const Gemm g, const Sched& S, const Epi& E) {
;     ...
;         const bool has_next = S.next(ui + 1, nxt);
;         const char* nA = has_next ? (const char*)g.A + (size_t)nxt.pm * tstepA : cA; const char* nB = has_next ? (const char*)g.Bt + (size_t)nxt.pn * tstepB : cB;
;     ...
;             PG8_LDB(B0, 0, 0); PG8_LDB(B1, 0, 1); PG8_SCHED; PG8_LDA(At, 0, 0); PG8_STAGE(PG8_SA(1, 1), a1 + hstepA, voffA);
;             PG8_WAIT_V(8); PG8_WAIT_L(0); PG8_BAR; PG8_MMA(0, 0, At, B0); PG8_MMA(0, 1, At, B1); PG8_BAR; PG8_SCHED;
;             PG8_LDA(At, 0, 1); PG8_STAGE(PG8_SB(0, 0), b2, voffB); PG8_STAGE(PG8_SB(0, 1), b2 + hstepB, voffB); PG8_STAGE(PG8_SA(0, 0), a2, voffA);
;             PG8_WAIT_V(8); PG8_WAIT_L(0); PG8_BAR; PG8_MMA(1, 0, At, B0); PG8_MMA(1, 1, At, B1); PG8_BAR; PG8_SCHED;
.LBB0_138:
	s_add_u32 s70, s70, 0x10000
	s_addc_u32 s71, s71, 0
	s_add_u32 s72, s72, 0x10000
	s_addc_u32 s73, s73, 0
	s_mov_b32 s94, -2
	ds_read_b128 v[150:153], v143
	ds_read_b128 v[154:157], v143 offset:1024
	ds_read_b128 v[158:161], v143 offset:2048
	ds_read_b128 v[162:165], v143 offset:3072
	ds_read_b128 v[166:169], v144
	ds_read_b128 v[170:173], v144 offset:1024
	ds_read_b128 v[174:177], v144 offset:2048
	ds_read_b128 v[178:181], v144 offset:3072
	s_cmp_eq_u32 s94, 12
	s_cselect_b32 s97, s59, s71
	s_cselect_b32 s96, s92, s70
	s_cselect_b32 vcc_hi, s57, s73
	s_cselect_b32 vcc_lo, s93, s72
	s_movk_i32 s8, 0xc000
	v_lshl_add_u64 v[186:187], s[70:71], 0, v[128:129]
	s_mov_b32 s9, -1
	v_lshl_add_u64 v[220:221], v[186:187], 0, s[8:9]
	s_movk_i32 s8, 0xe000
	s_add_i32 m0, s18, 0xc000
	s_mov_b32 s9, -1
	ds_read_b128 v[182:185], v145
	ds_read_b128 v[190:193], v145 offset:1024
	ds_read_b128 v[194:197], v145 offset:2048
	ds_read_b128 v[198:201], v145 offset:3072
	ds_read_b128 v[202:205], v145 offset:4096
	ds_read_b128 v[206:209], v145 offset:5120
	ds_read_b128 v[210:213], v145 offset:6144
	ds_read_b128 v[214:217], v145 offset:7168
	global_load_lds_dwordx4 v[220:221], off
	v_lshl_add_u64 v[186:187], v[186:187], 0, s[8:9]
	s_add_i32 m0, s18, 0xe000
	s_nop 0
	global_load_lds_dwordx4 v[186:187], off
	s_waitcnt vmcnt(8)
	s_waitcnt lgkmcnt(0)
	s_barrier
	s_waitcnt lgkmcnt(0)
	v_mfma_f32_16x16x32_bf16 v[116:119], v[150:153], v[182:185], 0
	v_mfma_f32_16x16x32_bf16 v[112:115], v[158:161], v[182:185], 0
	v_mfma_f32_16x16x32_bf16 v[108:111], v[150:153], v[194:197], 0
	v_mfma_f32_16x16x32_bf16 v[100:103], v[158:161], v[194:197], 0
	v_mfma_f32_16x16x32_bf16 v[92:95], v[150:153], v[202:205], 0
	v_mfma_f32_16x16x32_bf16 v[84:87], v[158:161], v[202:205], 0
	v_mfma_f32_16x16x32_bf16 v[76:79], v[150:153], v[210:213], 0
	v_mfma_f32_16x16x32_bf16 v[68:71], v[158:161], v[210:213], 0
	v_mfma_f32_16x16x32_bf16 v[116:119], v[154:157], v[190:193], v[116:119]
	v_mfma_f32_16x16x32_bf16 v[112:115], v[162:165], v[190:193], v[112:115]
	v_mfma_f32_16x16x32_bf16 v[108:111], v[154:157], v[198:201], v[108:111]
	v_mfma_f32_16x16x32_bf16 v[100:103], v[162:165], v[198:201], v[100:103]
	v_mfma_f32_16x16x32_bf16 v[92:95], v[154:157], v[206:209], v[92:95]
	v_mfma_f32_16x16x32_bf16 v[84:87], v[162:165], v[206:209], v[84:87]
	v_mfma_f32_16x16x32_bf16 v[76:79], v[154:157], v[214:217], v[76:79]
	v_mfma_f32_16x16x32_bf16 v[68:71], v[162:165], v[214:217], v[68:71]
	v_mfma_f32_16x16x32_bf16 v[124:127], v[166:169], v[182:185], 0
	v_mfma_f32_16x16x32_bf16 v[120:123], v[174:177], v[182:185], 0
	v_mfma_f32_16x16x32_bf16 v[104:107], v[166:169], v[194:197], 0
	v_mfma_f32_16x16x32_bf16 v[96:99], v[174:177], v[194:197], 0
	v_mfma_f32_16x16x32_bf16 v[88:91], v[166:169], v[202:205], 0
	v_mfma_f32_16x16x32_bf16 v[80:83], v[174:177], v[202:205], 0
	v_mfma_f32_16x16x32_bf16 v[72:75], v[166:169], v[210:213], 0
	v_mfma_f32_16x16x32_bf16 v[64:67], v[174:177], v[210:213], 0
	v_mfma_f32_16x16x32_bf16 v[124:127], v[170:173], v[190:193], v[124:127]
	v_mfma_f32_16x16x32_bf16 v[120:123], v[178:181], v[190:193], v[120:123]
	v_mfma_f32_16x16x32_bf16 v[104:107], v[170:173], v[198:201], v[104:107]
	v_mfma_f32_16x16x32_bf16 v[96:99], v[178:181], v[198:201], v[96:99]
	v_mfma_f32_16x16x32_bf16 v[88:91], v[170:173], v[206:209], v[88:91]
	v_mfma_f32_16x16x32_bf16 v[80:83], v[178:181], v[206:209], v[80:83]
	v_mfma_f32_16x16x32_bf16 v[72:75], v[170:173], v[214:217], v[72:75]
	v_mfma_f32_16x16x32_bf16 v[64:67], v[178:181], v[214:217], v[64:67]
	s_barrier
	s_add_i32 s8, s86, s14
	v_lshl_add_u64 v[186:187], vcc, 0, v[128:129]
	s_mov_b32 m0, s8
	ds_read_b128 v[182:185], v145 offset:16384
	ds_read_b128 v[190:193], v145 offset:17408
	ds_read_b128 v[194:197], v145 offset:18432
	ds_read_b128 v[198:201], v145 offset:19456
	ds_read_b128 v[202:205], v145 offset:20480
	ds_read_b128 v[206:209], v145 offset:21504
	ds_read_b128 v[210:213], v145 offset:22528
	ds_read_b128 v[214:217], v145 offset:23552
	global_load_lds_dwordx4 v[186:187], off
	v_lshl_add_u64 v[220:221], v[186:187], 0, s[4:5]
	s_add_i32 m0, s8, 0x2000
	s_add_i32 s8, s89, s14
	global_load_lds_dwordx4 v[220:221], off
	v_lshl_add_u64 v[220:221], v[186:187], 0, s[6:7]
	s_mov_b32 m0, s8
	s_nop 0
	global_load_lds_dwordx4 v[220:221], off
	v_lshl_add_u64 v[220:221], v[186:187], 0, s[30:31]
	s_add_i32 m0, s8, 0x2000
	s_nop 0
	global_load_lds_dwordx4 v[220:221], off
	v_lshl_add_u64 v[220:221], s[96:97], 0, v[128:129]
	s_mov_b32 m0, s18
	v_lshl_add_u64 v[222:223], v[220:221], 0, s[4:5]
	global_load_lds_dwordx4 v[220:221], off
	s_mov_b32 m0, s19
	s_nop 0
	global_load_lds_dwordx4 v[222:223], off
	s_waitcnt vmcnt(8)
	s_waitcnt lgkmcnt(0)
	s_barrier
; #define PG8_STAGE(bufoff, gbase, voff) do { _Pragma("unroll") for (int _i = 0; _i < 2; ++_i) \
;         __builtin_amdgcn_global_load_lds((const unsigned*)((const char*)(gbase) + (voff)[_i]), (PG8_LAS unsigned*)(lds + (bufoff) + ldsw + _i * 8192), 16, 0, 0); } while (0)
; #define PG8_LDA(dst, b, h) do { _Pragma("unroll") for (int m = 0; m < 4; ++m) _Pragma("unroll") for (int k = 0; k < 2; ++k) dst[m][k] = *(const PG8_LAS bf16x8*)(lds + PG8_SA(b, h) + aoff + m * 2048 + k * 1024); } while (0)
; #define PG8_LDB(dst, b, h) do { _Pragma("unroll") for (int n = 0; n < 2; ++n) _Pragma("unroll") for (int k = 0; k < 2; ++k) dst[n][k] = *(const PG8_LAS bf16x8*)(lds + PG8_SB(b, h) + boff + n * 2048 + k * 1024); } while (0)
; #define PG8_MMA(ai, bj, At, Bt) do { __builtin_amdgcn_s_setprio(1); _Pragma("unroll") for (int m = 0; m < 4; ++m) _Pragma("unroll") for (int n = 0; n < 2; ++n) _Pragma("unroll") for (int k = 0; k < 2; ++k) \
;         acc[ai][bj][m][n] = __builtin_amdgcn_mfma_f32_16x16x32_bf16(Bt[n][k], At[m][k], acc[ai][bj][m][n], 0, 0, 0); __builtin_amdgcn_s_setprio(0); } while (0)
; #define PG8_WAIT_V(n) asm volatile("s_waitcnt vmcnt(" #n ")" ::: "memory")
; #define PG8_WAIT_L(n) asm volatile("s_waitcnt lgkmcnt(" #n ")" ::: "memory")
; #define PG8_BAR __builtin_amdgcn_s_barrier()
; #define PG8_SCHED __builtin_amdgcn_sched_barrier(0)
; template <class Epi, class Sched, bool ALIGN_EPI = false, bool SP2 = false>
; __device__ __forceinline__ void gemm_phase(PG8_LAS unsigned char* lds, const Gemm g, const Sched& S, const Epi& E) {
;     ...
;             PG8_WAIT_V(8); PG8_WAIT_L(0); PG8_BAR; PG8_MMA(1, 0, At, B0); PG8_MMA(1, 1, At, B1); PG8_BAR; PG8_SCHED;
;             PG8_LDB(B0, 1, 0); PG8_LDB(B1, 1, 1); PG8_SCHED; PG8_LDA(At, 1, 0); PG8_STAGE(PG8_SA(0, 1), a2 + hstepA, voffA);
;             PG8_WAIT_V(8); PG8_WAIT_L(0); PG8_BAR; PG8_MMA(0, 0, At, B0); PG8_MMA(0, 1, At, B1); PG8_BAR; PG8_SCHED;
	s_waitcnt lgkmcnt(0)
	v_mfma_f32_16x16x32_bf16 v[60:63], v[150:153], v[182:185], 0
	v_mfma_f32_16x16x32_bf16 v[52:55], v[158:161], v[182:185], 0
	v_mfma_f32_16x16x32_bf16 v[44:47], v[150:153], v[194:197], 0
	v_mfma_f32_16x16x32_bf16 v[36:39], v[158:161], v[194:197], 0
	v_mfma_f32_16x16x32_bf16 v[28:31], v[150:153], v[202:205], 0
	v_mfma_f32_16x16x32_bf16 v[20:23], v[158:161], v[202:205], 0
	v_mfma_f32_16x16x32_bf16 v[12:15], v[150:153], v[210:213], 0
	v_mfma_f32_16x16x32_bf16 v[4:7], v[158:161], v[210:213], 0
	v_mfma_f32_16x16x32_bf16 v[60:63], v[154:157], v[190:193], v[60:63]
	v_mfma_f32_16x16x32_bf16 v[52:55], v[162:165], v[190:193], v[52:55]
	v_mfma_f32_16x16x32_bf16 v[44:47], v[154:157], v[198:201], v[44:47]
	v_mfma_f32_16x16x32_bf16 v[36:39], v[162:165], v[198:201], v[36:39]
	v_mfma_f32_16x16x32_bf16 v[28:31], v[154:157], v[206:209], v[28:31]
	v_mfma_f32_16x16x32_bf16 v[20:23], v[162:165], v[206:209], v[20:23]
	v_mfma_f32_16x16x32_bf16 v[12:15], v[154:157], v[214:217], v[12:15]
	v_mfma_f32_16x16x32_bf16 v[4:7], v[162:165], v[214:217], v[4:7]
	v_mfma_f32_16x16x32_bf16 v[56:59], v[166:169], v[182:185], 0
	v_mfma_f32_16x16x32_bf16 v[48:51], v[174:177], v[182:185], 0
	v_mfma_f32_16x16x32_bf16 v[40:43], v[166:169], v[194:197], 0
	v_mfma_f32_16x16x32_bf16 v[32:35], v[174:177], v[194:197], 0
	v_mfma_f32_16x16x32_bf16 v[24:27], v[166:169], v[202:205], 0
	v_mfma_f32_16x16x32_bf16 v[16:19], v[174:177], v[202:205], 0
	v_mfma_f32_16x16x32_bf16 v[8:11], v[166:169], v[210:213], 0
	v_mfma_f32_16x16x32_bf16 v[0:3], v[174:177], v[210:213], 0
	v_mfma_f32_16x16x32_bf16 v[56:59], v[170:173], v[190:193], v[56:59]
	v_mfma_f32_16x16x32_bf16 v[48:51], v[178:181], v[190:193], v[48:51]
	v_mfma_f32_16x16x32_bf16 v[40:43], v[170:173], v[198:201], v[40:43]
	v_mfma_f32_16x16x32_bf16 v[32:35], v[178:181], v[198:201], v[32:35]
	v_mfma_f32_16x16x32_bf16 v[24:27], v[170:173], v[206:209], v[24:27]
	v_mfma_f32_16x16x32_bf16 v[16:19], v[178:181], v[206:209], v[16:19]
	v_mfma_f32_16x16x32_bf16 v[8:11], v[170:173], v[214:217], v[8:11]
	v_mfma_f32_16x16x32_bf16 v[0:3], v[178:181], v[214:217], v[0:3]
	s_barrier
	ds_read_b128 v[150:153], v146
	ds_read_b128 v[154:157], v146 offset:1024
	ds_read_b128 v[158:161], v146 offset:2048
	ds_read_b128 v[162:165], v146 offset:3072
	ds_read_b128 v[166:169], v147
	ds_read_b128 v[170:173], v147 offset:1024
	ds_read_b128 v[174:177], v147 offset:2048
	ds_read_b128 v[178:181], v147 offset:3072
	s_mov_b32 m0, s74
	v_lshl_add_u64 v[222:223], v[220:221], 0, s[6:7]
	ds_read_b128 v[182:185], v145 offset:32768
	ds_read_b128 v[190:193], v145 offset:33792
	ds_read_b128 v[194:197], v145 offset:34816
	ds_read_b128 v[198:201], v145 offset:35840
	ds_read_b128 v[202:205], v145 offset:36864
	ds_read_b128 v[206:209], v145 offset:37888
	ds_read_b128 v[210:213], v145 offset:38912
	ds_read_b128 v[214:217], v145 offset:39936
	global_load_lds_dwordx4 v[222:223], off
	v_lshl_add_u64 v[222:223], v[220:221], 0, s[30:31]
	s_mov_b32 m0, s75
	s_nop 0
	global_load_lds_dwordx4 v[222:223], off
	s_waitcnt vmcnt(8)
	s_waitcnt lgkmcnt(0)
	s_barrier
	s_waitcnt lgkmcnt(0)
	v_mfma_f32_16x16x32_bf16 v[116:119], v[150:153], v[182:185], v[116:119]
	v_mfma_f32_16x16x32_bf16 v[112:115], v[158:161], v[182:185], v[112:115]
	v_mfma_f32_16x16x32_bf16 v[108:111], v[150:153], v[194:197], v[108:111]
	v_mfma_f32_16x16x32_bf16 v[100:103], v[158:161], v[194:197], v[100:103]
	v_mfma_f32_16x16x32_bf16 v[92:95], v[150:153], v[202:205], v[92:95]
	v_mfma_f32_16x16x32_bf16 v[84:87], v[158:161], v[202:205], v[84:87]
	v_mfma_f32_16x16x32_bf16 v[76:79], v[150:153], v[210:213], v[76:79]
	v_mfma_f32_16x16x32_bf16 v[68:71], v[158:161], v[210:213], v[68:71]
	v_mfma_f32_16x16x32_bf16 v[116:119], v[154:157], v[190:193], v[116:119]
	v_mfma_f32_16x16x32_bf16 v[112:115], v[162:165], v[190:193], v[112:115]
	v_mfma_f32_16x16x32_bf16 v[108:111], v[154:157], v[198:201], v[108:111]
	v_mfma_f32_16x16x32_bf16 v[100:103], v[162:165], v[198:201], v[100:103]
	v_mfma_f32_16x16x32_bf16 v[92:95], v[154:157], v[206:209], v[92:95]
	v_mfma_f32_16x16x32_bf16 v[84:87], v[162:165], v[206:209], v[84:87]
	v_mfma_f32_16x16x32_bf16 v[76:79], v[154:157], v[214:217], v[76:79]
	v_mfma_f32_16x16x32_bf16 v[68:71], v[162:165], v[214:217], v[68:71]
	v_mfma_f32_16x16x32_bf16 v[124:127], v[166:169], v[182:185], v[124:127]
	v_mfma_f32_16x16x32_bf16 v[120:123], v[174:177], v[182:185], v[120:123]
	v_mfma_f32_16x16x32_bf16 v[104:107], v[166:169], v[194:197], v[104:107]
	v_mfma_f32_16x16x32_bf16 v[96:99], v[174:177], v[194:197], v[96:99]
	v_mfma_f32_16x16x32_bf16 v[88:91], v[166:169], v[202:205], v[88:91]
	v_mfma_f32_16x16x32_bf16 v[80:83], v[174:177], v[202:205], v[80:83]
	v_mfma_f32_16x16x32_bf16 v[72:75], v[166:169], v[210:213], v[72:75]
	v_mfma_f32_16x16x32_bf16 v[64:67], v[174:177], v[210:213], v[64:67]
	v_mfma_f32_16x16x32_bf16 v[124:127], v[170:173], v[190:193], v[124:127]
	v_mfma_f32_16x16x32_bf16 v[120:123], v[178:181], v[190:193], v[120:123]
	v_mfma_f32_16x16x32_bf16 v[104:107], v[170:173], v[198:201], v[104:107]
	v_mfma_f32_16x16x32_bf16 v[96:99], v[178:181], v[198:201], v[96:99]
	v_mfma_f32_16x16x32_bf16 v[88:91], v[170:173], v[206:209], v[88:91]
	v_mfma_f32_16x16x32_bf16 v[80:83], v[178:181], v[206:209], v[80:83]
	v_mfma_f32_16x16x32_bf16 v[72:75], v[170:173], v[214:217], v[72:75]
	v_mfma_f32_16x16x32_bf16 v[64:67], v[178:181], v[214:217], v[64:67]
	s_barrier
; #define PG8_STAGE(bufoff, gbase, voff) do { _Pragma("unroll") for (int _i = 0; _i < 2; ++_i) \
;         __builtin_amdgcn_global_load_lds((const unsigned*)((const char*)(gbase) + (voff)[_i]), (PG8_LAS unsigned*)(lds + (bufoff) + ldsw + _i * 8192), 16, 0, 0); } while (0)
; #define PG8_LDA(dst, b, h) do { _Pragma("unroll") for (int m = 0; m < 4; ++m) _Pragma("unroll") for (int k = 0; k < 2; ++k) dst[m][k] = *(const PG8_LAS bf16x8*)(lds + PG8_SA(b, h) + aoff + m * 2048 + k * 1024); } while (0)
; #define PG8_MMA(ai, bj, At, Bt) do { __builtin_amdgcn_s_setprio(1); _Pragma("unroll") for (int m = 0; m < 4; ++m) _Pragma("unroll") for (int n = 0; n < 2; ++n) _Pragma("unroll") for (int k = 0; k < 2; ++k) \
;         acc[ai][bj][m][n] = __builtin_amdgcn_mfma_f32_16x16x32_bf16(Bt[n][k], At[m][k], acc[ai][bj][m][n], 0, 0, 0); __builtin_amdgcn_s_setprio(0); } while (0)
; #define PG8_WAIT_V(n) asm volatile("s_waitcnt vmcnt(" #n ")" ::: "memory")
; #define PG8_WAIT_L(n) asm volatile("s_waitcnt lgkmcnt(" #n ")" ::: "memory")
; #define PG8_BAR __builtin_amdgcn_s_barrier()
; #define PG8_SCHED __builtin_amdgcn_sched_barrier(0)
;     __host__ __device__ bool next(int i, Unit& u) const {
;         const long L = (long)i * G + c; if (L >= nwg) return false;
;         int wgid = (int)L; { const int q = nwg / NXCD, r = nwg % NXCD, xcd = wgid % NXCD, off = wgid / NXCD; wgid = (xcd < r ? xcd * (q + 1) : r * (q + 1) + (xcd - r) * q) + off; }
;         const int nig = wgm * nN, gid = wgid / nig, fm = gid * wgm, gsz = (nM - fm) < wgm ? (nM - fm) : wgm;
;         u.pm = fm + ((wgid % nig) % gsz); u.pn = (wgid % nig) / gsz; return true;
; template <class Epi, class Sched, bool ALIGN_EPI = false, bool SP2 = false>
; __device__ __forceinline__ void gemm_phase(PG8_LAS unsigned char* lds, const Gemm g, const Sched& S, const Epi& E) {
;     ...
;             PG8_LDA(At, 1, 1); PG8_STAGE(PG8_SB(1, 0), b3, voffB); PG8_STAGE(PG8_SB(1, 1), b3 + hstepB, voffB); PG8_STAGE(PG8_SA(1, 0), a3, voffA);
;             PG8_WAIT_V(8); PG8_WAIT_L(0); PG8_BAR; PG8_MMA(1, 0, At, B0); PG8_MMA(1, 1, At, B1); PG8_BAR; PG8_SCHED;
	s_add_i32 s8, s90, s14
	v_lshl_add_u64 v[222:223], v[186:187], 0, s[34:35]
	s_mov_b32 m0, s8
	ds_read_b128 v[182:185], v145 offset:49152
	ds_read_b128 v[190:193], v145 offset:50176
	ds_read_b128 v[194:197], v145 offset:51200
	ds_read_b128 v[198:201], v145 offset:52224
	ds_read_b128 v[202:205], v145 offset:53248
	ds_read_b128 v[206:209], v145 offset:54272
	ds_read_b128 v[210:213], v145 offset:55296
	ds_read_b128 v[214:217], v145 offset:56320
	global_load_lds_dwordx4 v[222:223], off
	v_lshl_add_u64 v[222:223], v[186:187], 0, s[36:37]
	s_add_i32 m0, s8, 0x2000
	s_add_i32 s8, s91, s14
	global_load_lds_dwordx4 v[222:223], off
	v_lshl_add_u64 v[222:223], v[186:187], 0, s[38:39]
	s_mov_b32 m0, s8
	v_lshl_add_u64 v[186:187], v[186:187], 0, s[40:41]
	global_load_lds_dwordx4 v[222:223], off
	s_add_i32 m0, s8, 0x2000
	s_nop 0
	global_load_lds_dwordx4 v[186:187], off
	v_lshl_add_u64 v[186:187], v[220:221], 0, s[34:35]
	s_mov_b32 m0, s76
	s_nop 0
	global_load_lds_dwordx4 v[186:187], off
	v_lshl_add_u64 v[186:187], v[220:221], 0, s[36:37]
	s_mov_b32 m0, s77
	s_nop 0
	global_load_lds_dwordx4 v[186:187], off
	s_waitcnt vmcnt(8)
	s_waitcnt lgkmcnt(0)
	s_barrier
	s_waitcnt lgkmcnt(0)
	v_mfma_f32_16x16x32_bf16 v[60:63], v[150:153], v[182:185], v[60:63]
	v_mfma_f32_16x16x32_bf16 v[52:55], v[158:161], v[182:185], v[52:55]
	v_mfma_f32_16x16x32_bf16 v[44:47], v[150:153], v[194:197], v[44:47]
	v_mfma_f32_16x16x32_bf16 v[36:39], v[158:161], v[194:197], v[36:39]
	v_mfma_f32_16x16x32_bf16 v[28:31], v[150:153], v[202:205], v[28:31]
	v_mfma_f32_16x16x32_bf16 v[20:23], v[158:161], v[202:205], v[20:23]
	v_mfma_f32_16x16x32_bf16 v[12:15], v[150:153], v[210:213], v[12:15]
	v_mfma_f32_16x16x32_bf16 v[4:7], v[158:161], v[210:213], v[4:7]
	v_mfma_f32_16x16x32_bf16 v[60:63], v[154:157], v[190:193], v[60:63]
	v_mfma_f32_16x16x32_bf16 v[52:55], v[162:165], v[190:193], v[52:55]
	v_mfma_f32_16x16x32_bf16 v[44:47], v[154:157], v[198:201], v[44:47]
	v_mfma_f32_16x16x32_bf16 v[36:39], v[162:165], v[198:201], v[36:39]
	v_mfma_f32_16x16x32_bf16 v[28:31], v[154:157], v[206:209], v[28:31]
	v_mfma_f32_16x16x32_bf16 v[20:23], v[162:165], v[206:209], v[20:23]
	v_mfma_f32_16x16x32_bf16 v[12:15], v[154:157], v[214:217], v[12:15]
	v_mfma_f32_16x16x32_bf16 v[4:7], v[162:165], v[214:217], v[4:7]
	v_mfma_f32_16x16x32_bf16 v[56:59], v[166:169], v[182:185], v[56:59]
	v_mfma_f32_16x16x32_bf16 v[48:51], v[174:177], v[182:185], v[48:51]
	v_mfma_f32_16x16x32_bf16 v[40:43], v[166:169], v[194:197], v[40:43]
	v_mfma_f32_16x16x32_bf16 v[32:35], v[174:177], v[194:197], v[32:35]
	v_mfma_f32_16x16x32_bf16 v[24:27], v[166:169], v[202:205], v[24:27]
	v_mfma_f32_16x16x32_bf16 v[16:19], v[174:177], v[202:205], v[16:19]
	v_mfma_f32_16x16x32_bf16 v[8:11], v[166:169], v[210:213], v[8:11]
	v_mfma_f32_16x16x32_bf16 v[0:3], v[174:177], v[210:213], v[0:3]
	v_mfma_f32_16x16x32_bf16 v[56:59], v[170:173], v[190:193], v[56:59]
	v_mfma_f32_16x16x32_bf16 v[48:51], v[178:181], v[190:193], v[48:51]
	v_mfma_f32_16x16x32_bf16 v[40:43], v[170:173], v[198:201], v[40:43]
	v_mfma_f32_16x16x32_bf16 v[32:35], v[178:181], v[198:201], v[32:35]
	v_mfma_f32_16x16x32_bf16 v[24:27], v[170:173], v[206:209], v[24:27]
	v_mfma_f32_16x16x32_bf16 v[16:19], v[178:181], v[206:209], v[16:19]
	v_mfma_f32_16x16x32_bf16 v[8:11], v[170:173], v[214:217], v[8:11]
	v_mfma_f32_16x16x32_bf16 v[0:3], v[178:181], v[214:217], v[0:3]
	s_barrier
	s_add_i32 s94, s94, 2
	s_add_u32 s70, s70, 0x10000
	s_addc_u32 s71, s71, 0
	s_add_u32 s72, s72, 0x10000
	s_addc_u32 s73, s73, 0
	s_cmp_gt_u32 s94, 13
	s_add_i32 s78, s78, 1
	s_mul_i32 s2, s78, s82
	s_mul_hi_u32 s3, s78, s85
	s_add_i32 s3, s3, s2
	s_mul_i32 s2, s78, s85
	s_add_u32 s60, s2, s16
	s_addc_u32 s61, s3, s15
	v_cmp_gt_i64_e32 vcc, s[60:61], v[140:141]
	v_cmp_lt_i64_e64 s[2:3], s[60:61], v[138:139]
	s_cbranch_vccnz .LBB0_140
	s_ashr_i32 s8, s60, 31
	s_lshr_b32 s8, s8, 29
	s_add_i32 s8, s60, s8
	s_ashr_i32 s9, s8, 3
	s_and_b32 s8, s8, -8
	s_sub_i32 s8, s60, s8
	s_cmp_lt_i32 s8, 0
	s_cselect_b32 s33, s17, 0x160
	s_mul_i32 s8, s8, s33
	s_add_i32 s8, s8, s9
	s_mul_hi_i32 s9, s8, 0x2e8ba2e9
	s_lshr_b32 s33, s9, 31
	s_ashr_i32 s9, s9, 4
	s_add_i32 s9, s9, s33
	s_lshl_b32 s33, s9, 2
	s_mulk_i32 s9, 0x58
	s_sub_i32 s8, s8, s9
	s_abs_i32 s9, s8
	s_ashr_i32 s56, s8, 2
	s_and_b32 s8, s8, 3
	s_add_i32 s58, s33, s8
.LBB0_140:
	s_ashr_i32 s59, s58, 31
	s_lshl_b64 s[60:61], s[58:59], 19
	s_add_u32 s60, s12, s60
	s_addc_u32 s61, s13, s61
	s_and_b64 s[62:63], s[2:3], exec
	s_cselect_b32 s59, s61, s71
	s_cselect_b32 s92, s60, s70
	s_ashr_i32 s57, s56, 31
	s_lshl_b64 s[62:63], s[56:57], 19
	s_add_u32 s62, s80, s62
	s_addc_u32 s63, s81, s63
	s_and_b64 s[98:99], s[2:3], exec
	s_cselect_b32 s57, s63, s73
	s_cselect_b32 s93, s62, s72

; #define PG8_STAGE(bufoff, gbase, voff) do { _Pragma("unroll") for (int _i = 0; _i < 2; ++_i) \
;         __builtin_amdgcn_global_load_lds((const unsigned*)((const char*)(gbase) + (voff)[_i]), (PG8_LAS unsigned*)(lds + (bufoff) + ldsw + _i * 8192), 16, 0, 0); } while (0)
; #define PG8_LDA(dst, b, h) do { _Pragma("unroll") for (int m = 0; m < 4; ++m) _Pragma("unroll") for (int k = 0; k < 2; ++k) dst[m][k] = *(const PG8_LAS bf16x8*)(lds + PG8_SA(b, h) + aoff + m * 2048 + k * 1024); } while (0)
; #define PG8_LDB(dst, b, h) do { _Pragma("unroll") for (int n = 0; n < 2; ++n) _Pragma("unroll") for (int k = 0; k < 2; ++k) dst[n][k] = *(const PG8_LAS bf16x8*)(lds + PG8_SB(b, h) + boff + n * 2048 + k * 1024); } while (0)
; #define PG8_MMA(ai, bj, At, Bt) do { __builtin_amdgcn_s_setprio(1); _Pragma("unroll") for (int m = 0; m < 4; ++m) _Pragma("unroll") for (int n = 0; n < 2; ++n) _Pragma("unroll") for (int k = 0; k < 2; ++k) \
;         acc[ai][bj][m][n] = __builtin_amdgcn_mfma_f32_16x16x32_bf16(Bt[n][k], At[m][k], acc[ai][bj][m][n], 0, 0, 0); __builtin_amdgcn_s_setprio(0); } while (0)
; #define PG8_WAIT_V(n) asm volatile("s_waitcnt vmcnt(" #n ")" ::: "memory")
; #define PG8_WAIT_L(n) asm volatile("s_waitcnt lgkmcnt(" #n ")" ::: "memory")
; #define PG8_BAR __builtin_amdgcn_s_barrier()
; #define PG8_SCHED __builtin_amdgcn_sched_barrier(0)
; template <class Epi, class Sched, bool ALIGN_EPI = false, bool SP2 = false>
; __device__ __forceinline__ void gemm_phase(PG8_LAS unsigned char* lds, const Gemm g, const Sched& S, const Epi& E) {
;     ...
;         const bool has_next = S.next(ui + 1, nxt);
;         const char* nA = has_next ? (const char*)g.A + (size_t)nxt.pm * tstepA : cA; const char* nB = has_next ? (const char*)g.Bt + (size_t)nxt.pn * tstepB : cB;
;     ...
;             PG8_LDB(B0, 0, 0); PG8_LDB(B1, 0, 1); PG8_SCHED; PG8_LDA(At, 0, 0); PG8_STAGE(PG8_SA(1, 1), a1 + hstepA, voffA);
;             PG8_WAIT_V(8); PG8_WAIT_L(0); PG8_BAR; PG8_MMA(0, 0, At, B0); PG8_MMA(0, 1, At, B1); PG8_BAR; PG8_SCHED;
;             PG8_LDA(At, 0, 1); PG8_STAGE(PG8_SB(0, 0), b2, voffB); PG8_STAGE(PG8_SB(0, 1), b2 + hstepB, voffB); PG8_STAGE(PG8_SA(0, 0), a2, voffA);
;             PG8_WAIT_V(8); PG8_WAIT_L(0); PG8_BAR; PG8_MMA(1, 0, At, B0); PG8_MMA(1, 1, At, B1); PG8_BAR; PG8_SCHED;
.LBB0_312:
	s_add_u32 s4, s4, 0x10000
	s_addc_u32 s5, s5, 0
	s_add_u32 s74, s74, 0x10000
	s_addc_u32 s75, s75, 0
	s_mov_b32 s76, -2
	ds_read_b128 v[140:143], v159
	ds_read_b128 v[144:147], v159 offset:1024
	ds_read_b128 v[148:151], v159 offset:2048
	ds_read_b128 v[166:169], v159 offset:3072
	ds_read_b128 v[170:173], v160
	ds_read_b128 v[174:177], v160 offset:1024
	ds_read_b128 v[178:181], v160 offset:2048
	ds_read_b128 v[182:185], v160 offset:3072
	s_cmp_eq_u32 s76, 12
	s_cselect_b32 s9, s7, s5
	s_cselect_b32 s8, s63, s4
	s_cselect_b32 vcc_hi, s61, s75
	s_cselect_b32 vcc_lo, s73, s74
	s_movk_i32 s78, 0xc000
	v_lshl_add_u64 v[2:3], s[4:5], 0, v[132:133]
	s_mov_b32 s79, -1
	v_lshl_add_u64 v[152:153], v[2:3], 0, s[78:79]
	s_movk_i32 s78, 0xe000
	s_add_i32 m0, s90, 0xc000
	s_mov_b32 s79, -1
	ds_read_b128 v[190:193], v161
	ds_read_b128 v[194:197], v161 offset:1024
	ds_read_b128 v[198:201], v161 offset:2048
	ds_read_b128 v[202:205], v161 offset:3072
	ds_read_b128 v[206:209], v161 offset:4096
	ds_read_b128 v[210:213], v161 offset:5120
	ds_read_b128 v[214:217], v161 offset:6144
	ds_read_b128 v[220:223], v161 offset:7168
	global_load_lds_dwordx4 v[152:153], off
	v_lshl_add_u64 v[2:3], v[2:3], 0, s[78:79]
	s_add_i32 m0, s90, 0xe000
	s_nop 0
	global_load_lds_dwordx4 v[2:3], off
	s_waitcnt vmcnt(8)
	s_waitcnt lgkmcnt(0)
	s_barrier
	s_waitcnt lgkmcnt(0)
	v_mfma_f32_16x16x32_bf16 v[128:131], v[140:143], v[190:193], 0
	v_mfma_f32_16x16x32_bf16 v[124:127], v[148:151], v[190:193], 0
	v_mfma_f32_16x16x32_bf16 v[112:115], v[140:143], v[198:201], 0
	v_mfma_f32_16x16x32_bf16 v[108:111], v[148:151], v[198:201], 0
	v_mfma_f32_16x16x32_bf16 v[96:99], v[140:143], v[206:209], 0
	v_mfma_f32_16x16x32_bf16 v[92:95], v[148:151], v[206:209], 0
	v_mfma_f32_16x16x32_bf16 v[80:83], v[140:143], v[214:217], 0
	v_mfma_f32_16x16x32_bf16 v[76:79], v[148:151], v[214:217], 0
	v_mfma_f32_16x16x32_bf16 v[128:131], v[144:147], v[194:197], v[128:131]
	v_mfma_f32_16x16x32_bf16 v[124:127], v[166:169], v[194:197], v[124:127]
	v_mfma_f32_16x16x32_bf16 v[112:115], v[144:147], v[202:205], v[112:115]
	v_mfma_f32_16x16x32_bf16 v[108:111], v[166:169], v[202:205], v[108:111]
	v_mfma_f32_16x16x32_bf16 v[96:99], v[144:147], v[210:213], v[96:99]
	v_mfma_f32_16x16x32_bf16 v[92:95], v[166:169], v[210:213], v[92:95]
	v_mfma_f32_16x16x32_bf16 v[80:83], v[144:147], v[220:223], v[80:83]
	v_mfma_f32_16x16x32_bf16 v[76:79], v[166:169], v[220:223], v[76:79]
	v_mfma_f32_16x16x32_bf16 v[120:123], v[170:173], v[190:193], 0
	v_mfma_f32_16x16x32_bf16 v[116:119], v[178:181], v[190:193], 0
	v_mfma_f32_16x16x32_bf16 v[104:107], v[170:173], v[198:201], 0
	v_mfma_f32_16x16x32_bf16 v[100:103], v[178:181], v[198:201], 0
	v_mfma_f32_16x16x32_bf16 v[88:91], v[170:173], v[206:209], 0
	v_mfma_f32_16x16x32_bf16 v[84:87], v[178:181], v[206:209], 0
	v_mfma_f32_16x16x32_bf16 v[72:75], v[170:173], v[214:217], 0
	v_mfma_f32_16x16x32_bf16 v[68:71], v[178:181], v[214:217], 0
	v_mfma_f32_16x16x32_bf16 v[120:123], v[174:177], v[194:197], v[120:123]
	v_mfma_f32_16x16x32_bf16 v[116:119], v[182:185], v[194:197], v[116:119]
	v_mfma_f32_16x16x32_bf16 v[104:107], v[174:177], v[202:205], v[104:107]
	v_mfma_f32_16x16x32_bf16 v[100:103], v[182:185], v[202:205], v[100:103]
	v_mfma_f32_16x16x32_bf16 v[88:91], v[174:177], v[210:213], v[88:91]
	v_mfma_f32_16x16x32_bf16 v[84:87], v[182:185], v[210:213], v[84:87]
	v_mfma_f32_16x16x32_bf16 v[72:75], v[174:177], v[220:223], v[72:75]
	v_mfma_f32_16x16x32_bf16 v[68:71], v[182:185], v[220:223], v[68:71]
	s_barrier
	s_add_i32 s77, s15, s89
	v_lshl_add_u64 v[152:153], vcc, 0, v[132:133]
	s_mov_b32 m0, s77
	ds_read_b128 v[190:193], v161 offset:16384
	ds_read_b128 v[194:197], v161 offset:17408
	ds_read_b128 v[198:201], v161 offset:18432
	ds_read_b128 v[202:205], v161 offset:19456
	ds_read_b128 v[206:209], v161 offset:20480
	ds_read_b128 v[210:213], v161 offset:21504
	ds_read_b128 v[214:217], v161 offset:22528
	ds_read_b128 v[220:223], v161 offset:23552
	global_load_lds_dwordx4 v[152:153], off
	v_lshl_add_u64 v[2:3], v[152:153], 0, s[30:31]
	s_add_i32 m0, s77, 0x2000
	s_add_i32 s77, s18, s89
	global_load_lds_dwordx4 v[2:3], off
	v_lshl_add_u64 v[2:3], v[152:153], 0, s[34:35]
	s_mov_b32 m0, s77
	v_lshl_add_u64 v[186:187], s[8:9], 0, v[132:133]
	global_load_lds_dwordx4 v[2:3], off
	v_lshl_add_u64 v[2:3], v[152:153], 0, s[36:37]
	s_add_i32 m0, s77, 0x2000
	s_nop 0
	global_load_lds_dwordx4 v[2:3], off
	s_mov_b32 m0, s90
	v_lshl_add_u64 v[2:3], v[186:187], 0, s[30:31]
	global_load_lds_dwordx4 v[186:187], off
	s_mov_b32 m0, s91
	s_nop 0
	global_load_lds_dwordx4 v[2:3], off
	s_waitcnt vmcnt(8)
	s_waitcnt lgkmcnt(0)
	s_barrier
; #define PG8_STAGE(bufoff, gbase, voff) do { _Pragma("unroll") for (int _i = 0; _i < 2; ++_i) \
;         __builtin_amdgcn_global_load_lds((const unsigned*)((const char*)(gbase) + (voff)[_i]), (PG8_LAS unsigned*)(lds + (bufoff) + ldsw + _i * 8192), 16, 0, 0); } while (0)
; #define PG8_LDA(dst, b, h) do { _Pragma("unroll") for (int m = 0; m < 4; ++m) _Pragma("unroll") for (int k = 0; k < 2; ++k) dst[m][k] = *(const PG8_LAS bf16x8*)(lds + PG8_SA(b, h) + aoff + m * 2048 + k * 1024); } while (0)
; #define PG8_LDB(dst, b, h) do { _Pragma("unroll") for (int n = 0; n < 2; ++n) _Pragma("unroll") for (int k = 0; k < 2; ++k) dst[n][k] = *(const PG8_LAS bf16x8*)(lds + PG8_SB(b, h) + boff + n * 2048 + k * 1024); } while (0)
; #define PG8_MMA(ai, bj, At, Bt) do { __builtin_amdgcn_s_setprio(1); _Pragma("unroll") for (int m = 0; m < 4; ++m) _Pragma("unroll") for (int n = 0; n < 2; ++n) _Pragma("unroll") for (int k = 0; k < 2; ++k) \
;         acc[ai][bj][m][n] = __builtin_amdgcn_mfma_f32_16x16x32_bf16(Bt[n][k], At[m][k], acc[ai][bj][m][n], 0, 0, 0); __builtin_amdgcn_s_setprio(0); } while (0)
; #define PG8_WAIT_V(n) asm volatile("s_waitcnt vmcnt(" #n ")" ::: "memory")
; #define PG8_WAIT_L(n) asm volatile("s_waitcnt lgkmcnt(" #n ")" ::: "memory")
; #define PG8_BAR __builtin_amdgcn_s_barrier()
; #define PG8_SCHED __builtin_amdgcn_sched_barrier(0)
; template <class Epi, class Sched, bool ALIGN_EPI = false, bool SP2 = false>
; __device__ __forceinline__ void gemm_phase(PG8_LAS unsigned char* lds, const Gemm g, const Sched& S, const Epi& E) {
;     ...
;             PG8_WAIT_V(8); PG8_WAIT_L(0); PG8_BAR; PG8_MMA(1, 0, At, B0); PG8_MMA(1, 1, At, B1); PG8_BAR; PG8_SCHED;
;             PG8_LDB(B0, 1, 0); PG8_LDB(B1, 1, 1); PG8_SCHED; PG8_LDA(At, 1, 0); PG8_STAGE(PG8_SA(0, 1), a2 + hstepA, voffA);
;             PG8_WAIT_V(8); PG8_WAIT_L(0); PG8_BAR; PG8_MMA(0, 0, At, B0); PG8_MMA(0, 1, At, B1); PG8_BAR; PG8_SCHED;
	s_waitcnt lgkmcnt(0)
	v_mfma_f32_16x16x32_bf16 v[64:67], v[140:143], v[190:193], 0
	v_mfma_f32_16x16x32_bf16 v[60:63], v[148:151], v[190:193], 0
	v_mfma_f32_16x16x32_bf16 v[48:51], v[140:143], v[198:201], 0
	v_mfma_f32_16x16x32_bf16 v[44:47], v[148:151], v[198:201], 0
	v_mfma_f32_16x16x32_bf16 v[32:35], v[140:143], v[206:209], 0
	v_mfma_f32_16x16x32_bf16 v[28:31], v[148:151], v[206:209], 0
	v_mfma_f32_16x16x32_bf16 v[16:19], v[140:143], v[214:217], 0
	v_mfma_f32_16x16x32_bf16 v[12:15], v[148:151], v[214:217], 0
	v_mfma_f32_16x16x32_bf16 v[64:67], v[144:147], v[194:197], v[64:67]
	v_mfma_f32_16x16x32_bf16 v[60:63], v[166:169], v[194:197], v[60:63]
	v_mfma_f32_16x16x32_bf16 v[48:51], v[144:147], v[202:205], v[48:51]
	v_mfma_f32_16x16x32_bf16 v[44:47], v[166:169], v[202:205], v[44:47]
	v_mfma_f32_16x16x32_bf16 v[32:35], v[144:147], v[210:213], v[32:35]
	v_mfma_f32_16x16x32_bf16 v[28:31], v[166:169], v[210:213], v[28:31]
	v_mfma_f32_16x16x32_bf16 v[16:19], v[144:147], v[220:223], v[16:19]
	v_mfma_f32_16x16x32_bf16 v[12:15], v[166:169], v[220:223], v[12:15]
	v_mfma_f32_16x16x32_bf16 v[56:59], v[170:173], v[190:193], 0
	v_mfma_f32_16x16x32_bf16 v[52:55], v[178:181], v[190:193], 0
	v_mfma_f32_16x16x32_bf16 v[40:43], v[170:173], v[198:201], 0
	v_mfma_f32_16x16x32_bf16 v[36:39], v[178:181], v[198:201], 0
	v_mfma_f32_16x16x32_bf16 v[24:27], v[170:173], v[206:209], 0
	v_mfma_f32_16x16x32_bf16 v[20:23], v[178:181], v[206:209], 0
	v_mfma_f32_16x16x32_bf16 v[8:11], v[170:173], v[214:217], 0
	v_mfma_f32_16x16x32_bf16 v[2:5], v[178:181], v[214:217], 0
	v_mfma_f32_16x16x32_bf16 v[56:59], v[174:177], v[194:197], v[56:59]
	v_mfma_f32_16x16x32_bf16 v[52:55], v[182:185], v[194:197], v[52:55]
	v_mfma_f32_16x16x32_bf16 v[40:43], v[174:177], v[202:205], v[40:43]
	v_mfma_f32_16x16x32_bf16 v[36:39], v[182:185], v[202:205], v[36:39]
	v_mfma_f32_16x16x32_bf16 v[24:27], v[174:177], v[210:213], v[24:27]
	v_mfma_f32_16x16x32_bf16 v[20:23], v[182:185], v[210:213], v[20:23]
	v_mfma_f32_16x16x32_bf16 v[8:11], v[174:177], v[220:223], v[8:11]
	v_mfma_f32_16x16x32_bf16 v[2:5], v[182:185], v[220:223], v[2:5]
	s_barrier
	ds_read_b128 v[140:143], v162
	ds_read_b128 v[144:147], v162 offset:1024
	ds_read_b128 v[148:151], v162 offset:2048
	ds_read_b128 v[166:169], v162 offset:3072
	ds_read_b128 v[170:173], v163
	ds_read_b128 v[174:177], v163 offset:1024
	ds_read_b128 v[178:181], v163 offset:2048
	ds_read_b128 v[182:185], v163 offset:3072
	s_mov_b32 m0, s92
	v_lshl_add_u64 v[6:7], v[186:187], 0, s[34:35]
	ds_read_b128 v[190:193], v161 offset:32768
	ds_read_b128 v[194:197], v161 offset:33792
	ds_read_b128 v[198:201], v161 offset:34816
	ds_read_b128 v[202:205], v161 offset:35840
	ds_read_b128 v[206:209], v161 offset:36864
	ds_read_b128 v[210:213], v161 offset:37888
	ds_read_b128 v[214:217], v161 offset:38912
	ds_read_b128 v[220:223], v161 offset:39936
	global_load_lds_dwordx4 v[6:7], off
	v_lshl_add_u64 v[6:7], v[186:187], 0, s[36:37]
	s_mov_b32 m0, s93
	s_nop 0
	global_load_lds_dwordx4 v[6:7], off
	s_waitcnt vmcnt(8)
	s_waitcnt lgkmcnt(0)
	s_barrier
	s_waitcnt lgkmcnt(0)
	v_mfma_f32_16x16x32_bf16 v[128:131], v[140:143], v[190:193], v[128:131]
	v_mfma_f32_16x16x32_bf16 v[124:127], v[148:151], v[190:193], v[124:127]
	v_mfma_f32_16x16x32_bf16 v[112:115], v[140:143], v[198:201], v[112:115]
	v_mfma_f32_16x16x32_bf16 v[108:111], v[148:151], v[198:201], v[108:111]
	v_mfma_f32_16x16x32_bf16 v[96:99], v[140:143], v[206:209], v[96:99]
	v_mfma_f32_16x16x32_bf16 v[92:95], v[148:151], v[206:209], v[92:95]
	v_mfma_f32_16x16x32_bf16 v[80:83], v[140:143], v[214:217], v[80:83]
	v_mfma_f32_16x16x32_bf16 v[76:79], v[148:151], v[214:217], v[76:79]
	v_mfma_f32_16x16x32_bf16 v[128:131], v[144:147], v[194:197], v[128:131]
	v_mfma_f32_16x16x32_bf16 v[124:127], v[166:169], v[194:197], v[124:127]
	v_mfma_f32_16x16x32_bf16 v[112:115], v[144:147], v[202:205], v[112:115]
	v_mfma_f32_16x16x32_bf16 v[108:111], v[166:169], v[202:205], v[108:111]
	v_mfma_f32_16x16x32_bf16 v[96:99], v[144:147], v[210:213], v[96:99]
	v_mfma_f32_16x16x32_bf16 v[92:95], v[166:169], v[210:213], v[92:95]
	v_mfma_f32_16x16x32_bf16 v[80:83], v[144:147], v[220:223], v[80:83]
	v_mfma_f32_16x16x32_bf16 v[76:79], v[166:169], v[220:223], v[76:79]
	v_mfma_f32_16x16x32_bf16 v[120:123], v[170:173], v[190:193], v[120:123]
	v_mfma_f32_16x16x32_bf16 v[116:119], v[178:181], v[190:193], v[116:119]
	v_mfma_f32_16x16x32_bf16 v[104:107], v[170:173], v[198:201], v[104:107]
	v_mfma_f32_16x16x32_bf16 v[100:103], v[178:181], v[198:201], v[100:103]
	v_mfma_f32_16x16x32_bf16 v[88:91], v[170:173], v[206:209], v[88:91]
	v_mfma_f32_16x16x32_bf16 v[84:87], v[178:181], v[206:209], v[84:87]
	v_mfma_f32_16x16x32_bf16 v[72:75], v[170:173], v[214:217], v[72:75]
	v_mfma_f32_16x16x32_bf16 v[68:71], v[178:181], v[214:217], v[68:71]
	v_mfma_f32_16x16x32_bf16 v[120:123], v[174:177], v[194:197], v[120:123]
	v_mfma_f32_16x16x32_bf16 v[116:119], v[182:185], v[194:197], v[116:119]
	v_mfma_f32_16x16x32_bf16 v[104:107], v[174:177], v[202:205], v[104:107]
	v_mfma_f32_16x16x32_bf16 v[100:103], v[182:185], v[202:205], v[100:103]
	v_mfma_f32_16x16x32_bf16 v[88:91], v[174:177], v[210:213], v[88:91]
	v_mfma_f32_16x16x32_bf16 v[84:87], v[182:185], v[210:213], v[84:87]
	v_mfma_f32_16x16x32_bf16 v[72:75], v[174:177], v[220:223], v[72:75]
	v_mfma_f32_16x16x32_bf16 v[68:71], v[182:185], v[220:223], v[68:71]
	s_barrier
; #define PG8_STAGE(bufoff, gbase, voff) do { _Pragma("unroll") for (int _i = 0; _i < 2; ++_i) \
;         __builtin_amdgcn_global_load_lds((const unsigned*)((const char*)(gbase) + (voff)[_i]), (PG8_LAS unsigned*)(lds + (bufoff) + ldsw + _i * 8192), 16, 0, 0); } while (0)
; #define PG8_LDA(dst, b, h) do { _Pragma("unroll") for (int m = 0; m < 4; ++m) _Pragma("unroll") for (int k = 0; k < 2; ++k) dst[m][k] = *(const PG8_LAS bf16x8*)(lds + PG8_SA(b, h) + aoff + m * 2048 + k * 1024); } while (0)
; #define PG8_MMA(ai, bj, At, Bt) do { __builtin_amdgcn_s_setprio(1); _Pragma("unroll") for (int m = 0; m < 4; ++m) _Pragma("unroll") for (int n = 0; n < 2; ++n) _Pragma("unroll") for (int k = 0; k < 2; ++k) \
;         acc[ai][bj][m][n] = __builtin_amdgcn_mfma_f32_16x16x32_bf16(Bt[n][k], At[m][k], acc[ai][bj][m][n], 0, 0, 0); __builtin_amdgcn_s_setprio(0); } while (0)
; #define PG8_WAIT_V(n) asm volatile("s_waitcnt vmcnt(" #n ")" ::: "memory")
; #define PG8_WAIT_L(n) asm volatile("s_waitcnt lgkmcnt(" #n ")" ::: "memory")
; #define PG8_BAR __builtin_amdgcn_s_barrier()
; #define PG8_SCHED __builtin_amdgcn_sched_barrier(0)
;     __host__ __device__ bool next(int i, Unit& u) const {
;         const long L = (long)i * G + c; if (L >= nwg) return false;
;         int wgid = (int)L; { const int q = nwg / NXCD, r = nwg % NXCD, xcd = wgid % NXCD, off = wgid / NXCD; wgid = (xcd < r ? xcd * (q + 1) : r * (q + 1) + (xcd - r) * q) + off; }
;         const int nig = wgm * nN, gid = wgid / nig, fm = gid * wgm, gsz = (nM - fm) < wgm ? (nM - fm) : wgm;
;         u.pm = fm + ((wgid % nig) % gsz); u.pn = (wgid % nig) / gsz; return true;
; template <class Epi, class Sched, bool ALIGN_EPI = false, bool SP2 = false>
; __device__ __forceinline__ void gemm_phase(PG8_LAS unsigned char* lds, const Gemm g, const Sched& S, const Epi& E) {
;     ...
;             PG8_LDA(At, 1, 1); PG8_STAGE(PG8_SB(1, 0), b3, voffB); PG8_STAGE(PG8_SB(1, 1), b3 + hstepB, voffB); PG8_STAGE(PG8_SA(1, 0), a3, voffA);
;             PG8_WAIT_V(8); PG8_WAIT_L(0); PG8_BAR; PG8_MMA(1, 0, At, B0); PG8_MMA(1, 1, At, B1); PG8_BAR; PG8_SCHED;
	s_add_i32 s8, s19, s89
	v_lshl_add_u64 v[6:7], v[152:153], 0, s[38:39]
	s_mov_b32 m0, s8
	ds_read_b128 v[190:193], v161 offset:49152
	ds_read_b128 v[194:197], v161 offset:50176
	ds_read_b128 v[198:201], v161 offset:51200
	ds_read_b128 v[202:205], v161 offset:52224
	ds_read_b128 v[206:209], v161 offset:53248
	ds_read_b128 v[210:213], v161 offset:54272
	ds_read_b128 v[214:217], v161 offset:55296
	ds_read_b128 v[220:223], v161 offset:56320
	global_load_lds_dwordx4 v[6:7], off
	v_lshl_add_u64 v[6:7], v[152:153], 0, s[40:41]
	s_add_i32 m0, s8, 0x2000
	s_add_i32 s8, s80, s89
	global_load_lds_dwordx4 v[6:7], off
	v_lshl_add_u64 v[6:7], v[152:153], 0, s[52:53]
	s_mov_b32 m0, s8
	s_nop 0
	global_load_lds_dwordx4 v[6:7], off
	v_lshl_add_u64 v[6:7], v[152:153], 0, s[54:55]
	s_add_i32 m0, s8, 0x2000
	s_nop 0
	global_load_lds_dwordx4 v[6:7], off
	v_lshl_add_u64 v[6:7], v[186:187], 0, s[38:39]
	s_mov_b32 m0, s94
	s_nop 0
	global_load_lds_dwordx4 v[6:7], off
	v_lshl_add_u64 v[6:7], v[186:187], 0, s[40:41]
	s_mov_b32 m0, s95
	s_nop 0
	global_load_lds_dwordx4 v[6:7], off
	s_waitcnt vmcnt(8)
	s_waitcnt lgkmcnt(0)
	s_barrier
	s_waitcnt lgkmcnt(0)
	v_mfma_f32_16x16x32_bf16 v[64:67], v[140:143], v[190:193], v[64:67]
	v_mfma_f32_16x16x32_bf16 v[60:63], v[148:151], v[190:193], v[60:63]
	v_mfma_f32_16x16x32_bf16 v[48:51], v[140:143], v[198:201], v[48:51]
	v_mfma_f32_16x16x32_bf16 v[44:47], v[148:151], v[198:201], v[44:47]
	v_mfma_f32_16x16x32_bf16 v[32:35], v[140:143], v[206:209], v[32:35]
	v_mfma_f32_16x16x32_bf16 v[28:31], v[148:151], v[206:209], v[28:31]
	v_mfma_f32_16x16x32_bf16 v[16:19], v[140:143], v[214:217], v[16:19]
	v_mfma_f32_16x16x32_bf16 v[12:15], v[148:151], v[214:217], v[12:15]
	v_mfma_f32_16x16x32_bf16 v[64:67], v[144:147], v[194:197], v[64:67]
	v_mfma_f32_16x16x32_bf16 v[60:63], v[166:169], v[194:197], v[60:63]
	v_mfma_f32_16x16x32_bf16 v[48:51], v[144:147], v[202:205], v[48:51]
	v_mfma_f32_16x16x32_bf16 v[44:47], v[166:169], v[202:205], v[44:47]
	v_mfma_f32_16x16x32_bf16 v[32:35], v[144:147], v[210:213], v[32:35]
	v_mfma_f32_16x16x32_bf16 v[28:31], v[166:169], v[210:213], v[28:31]
	v_mfma_f32_16x16x32_bf16 v[16:19], v[144:147], v[220:223], v[16:19]
	v_mfma_f32_16x16x32_bf16 v[12:15], v[166:169], v[220:223], v[12:15]
	v_mfma_f32_16x16x32_bf16 v[56:59], v[170:173], v[190:193], v[56:59]
	v_mfma_f32_16x16x32_bf16 v[52:55], v[178:181], v[190:193], v[52:55]
	v_mfma_f32_16x16x32_bf16 v[40:43], v[170:173], v[198:201], v[40:43]
	v_mfma_f32_16x16x32_bf16 v[36:39], v[178:181], v[198:201], v[36:39]
	v_mfma_f32_16x16x32_bf16 v[24:27], v[170:173], v[206:209], v[24:27]
	v_mfma_f32_16x16x32_bf16 v[20:23], v[178:181], v[206:209], v[20:23]
	v_mfma_f32_16x16x32_bf16 v[6:9], v[170:173], v[214:217], v[8:11]
	v_mfma_f32_16x16x32_bf16 v[2:5], v[178:181], v[214:217], v[2:5]
	v_mfma_f32_16x16x32_bf16 v[56:59], v[174:177], v[194:197], v[56:59]
	v_mfma_f32_16x16x32_bf16 v[52:55], v[182:185], v[194:197], v[52:55]
	v_mfma_f32_16x16x32_bf16 v[40:43], v[174:177], v[202:205], v[40:43]
	v_mfma_f32_16x16x32_bf16 v[36:39], v[182:185], v[202:205], v[36:39]
	v_mfma_f32_16x16x32_bf16 v[24:27], v[174:177], v[210:213], v[24:27]
	v_mfma_f32_16x16x32_bf16 v[20:23], v[182:185], v[210:213], v[20:23]
	v_mfma_f32_16x16x32_bf16 v[8:11], v[174:177], v[220:223], v[6:9]
	v_mfma_f32_16x16x32_bf16 v[4:7], v[182:185], v[220:223], v[2:5]
	s_barrier
	s_add_i32 s76, s76, 2
	s_add_u32 s4, s4, 0x10000
	s_addc_u32 s5, s5, 0
	s_add_u32 s74, s74, 0x10000
	s_addc_u32 s75, s75, 0
	s_cmp_gt_u32 s76, 13
	s_add_i32 s96, s96, 1
	s_mul_i32 s2, s96, s97
	s_mul_hi_u32 s3, s96, s82
	s_add_i32 s3, s3, s2
	s_mul_i32 s2, s96, s82
	s_add_u32 s68, s2, s16
	s_addc_u32 s69, s3, s17
	v_cmp_gt_i64_e32 vcc, s[68:69], v[138:139]
	v_cmp_lt_i64_e64 s[2:3], s[68:69], v[136:137]
	s_cbranch_vccnz .LBB0_314
	s_ashr_i32 s7, s68, 31
	s_lshr_b32 s7, s7, 29
	s_add_i32 s7, s68, s7
	s_ashr_i32 s8, s7, 3
	s_and_b32 s7, s7, -8
	s_sub_i32 s7, s68, s7
	s_cmp_lt_i32 s7, 0
	s_movk_i32 s9, 0xf1
	s_cselect_b32 s9, s9, 0xf0
	s_mul_i32 s7, s7, s9
	s_add_i32 s7, s7, s8
	s_mul_hi_i32 s8, s7, 0x88888889
	s_add_i32 s8, s8, s7
	s_lshr_b32 s9, s8, 31
	s_ashr_i32 s8, s8, 5
	s_add_i32 s8, s8, s9
	s_lshl_b32 s9, s8, 2
	s_mul_i32 s8, s8, 60
	s_sub_i32 s7, s7, s8
	s_abs_i32 s8, s7
	s_ashr_i32 s60, s7, 2
	s_and_b32 s7, s7, 3
	s_add_i32 s62, s9, s7
.LBB0_314:
	s_ashr_i32 s63, s62, 31
	s_lshl_b64 s[8:9], s[62:63], 19
	s_add_u32 s68, s12, s8
	s_addc_u32 s69, s13, s9
	s_and_b64 s[8:9], s[2:3], exec
	s_cselect_b32 s7, s69, s5
	s_cselect_b32 s63, s68, s4
	s_ashr_i32 s61, s60, 31
	s_lshl_b64 s[8:9], s[60:61], 19
	s_add_u32 s70, s87, s8
	s_addc_u32 s71, s88, s9
	s_and_b64 s[8:9], s[2:3], exec
	s_cselect_b32 s61, s71, s75
	s_cselect_b32 s73, s70, s74
; #define PG8_STAGE(bufoff, gbase, voff) do { _Pragma("unroll") for (int _i = 0; _i < 2; ++_i) \
;         __builtin_amdgcn_global_load_lds((const unsigned*)((const char*)(gbase) + (voff)[_i]), (PG8_LAS unsigned*)(lds + (bufoff) + ldsw + _i * 8192), 16, 0, 0); } while (0)
; #define PG8_LDA(dst, b, h) do { _Pragma("unroll") for (int m = 0; m < 4; ++m) _Pragma("unroll") for (int k = 0; k < 2; ++k) dst[m][k] = *(const PG8_LAS bf16x8*)(lds + PG8_SA(b, h) + aoff + m * 2048 + k * 1024); } while (0)
; #define PG8_LDB(dst, b, h) do { _Pragma("unroll") for (int n = 0; n < 2; ++n) _Pragma("unroll") for (int k = 0; k < 2; ++k) dst[n][k] = *(const PG8_LAS bf16x8*)(lds + PG8_SB(b, h) + boff + n * 2048 + k * 1024); } while (0)
; #define PG8_MMA(ai, bj, At, Bt) do { __builtin_amdgcn_s_setprio(1); _Pragma("unroll") for (int m = 0; m < 4; ++m) _Pragma("unroll") for (int n = 0; n < 2; ++n) _Pragma("unroll") for (int k = 0; k < 2; ++k) \
;         acc[ai][bj][m][n] = __builtin_amdgcn_mfma_f32_16x16x32_bf16(Bt[n][k], At[m][k], acc[ai][bj][m][n], 0, 0, 0); __builtin_amdgcn_s_setprio(0); } while (0)
; #define PG8_WAIT_V(n) asm volatile("s_waitcnt vmcnt(" #n ")" ::: "memory")
; #define PG8_WAIT_L(n) asm volatile("s_waitcnt lgkmcnt(" #n ")" ::: "memory")
; #define PG8_BAR __builtin_amdgcn_s_barrier()
; #define PG8_SCHED __builtin_amdgcn_sched_barrier(0)
; template <class Epi, class Sched, bool ALIGN_EPI = false, bool SP2 = false>
; __device__ __forceinline__ void gemm_phase(PG8_LAS unsigned char* lds, const Gemm g, const Sched& S, const Epi& E) {
;     ...
;             PG8_LDB(B0, 0, 0); PG8_LDB(B1, 0, 1); PG8_SCHED; PG8_LDA(At, 0, 0); PG8_STAGE(PG8_SA(1, 1), a1 + hstepA, voffA);
;             PG8_WAIT_V(8); PG8_WAIT_L(0); PG8_BAR; PG8_MMA(0, 0, At, B0); PG8_MMA(0, 1, At, B1); PG8_BAR; PG8_SCHED;
;             PG8_LDA(At, 0, 1); PG8_STAGE(PG8_SB(0, 0), b2, voffB); PG8_STAGE(PG8_SB(0, 1), b2 + hstepB, voffB); PG8_STAGE(PG8_SA(0, 0), a2, voffA);
;             PG8_WAIT_V(8); PG8_WAIT_L(0); PG8_BAR; PG8_MMA(1, 0, At, B0); PG8_MMA(1, 1, At, B1); PG8_BAR; PG8_SCHED;
.LBB0_315:
	ds_read_b128 v[140:143], v159
	ds_read_b128 v[144:147], v159 offset:1024
	ds_read_b128 v[148:151], v159 offset:2048
	ds_read_b128 v[166:169], v159 offset:3072
	ds_read_b128 v[170:173], v160
	ds_read_b128 v[174:177], v160 offset:1024
	ds_read_b128 v[178:181], v160 offset:2048
	ds_read_b128 v[182:185], v160 offset:3072
	s_cmp_eq_u32 s76, 12
	s_cselect_b32 s9, s7, s5
	s_cselect_b32 s8, s63, s4
	s_cselect_b32 vcc_hi, s61, s75
	s_cselect_b32 vcc_lo, s73, s74
	s_movk_i32 s78, 0xc000
	v_lshl_add_u64 v[2:3], s[4:5], 0, v[132:133]
	s_mov_b32 s79, -1
	v_lshl_add_u64 v[152:153], v[2:3], 0, s[78:79]
	s_movk_i32 s78, 0xe000
	s_add_i32 m0, s90, 0xc000
	s_mov_b32 s79, -1
	ds_read_b128 v[190:193], v161
	ds_read_b128 v[194:197], v161 offset:1024
	ds_read_b128 v[198:201], v161 offset:2048
	ds_read_b128 v[202:205], v161 offset:3072
	ds_read_b128 v[206:209], v161 offset:4096
	ds_read_b128 v[210:213], v161 offset:5120
	ds_read_b128 v[214:217], v161 offset:6144
	ds_read_b128 v[220:223], v161 offset:7168
	global_load_lds_dwordx4 v[152:153], off
	v_lshl_add_u64 v[2:3], v[2:3], 0, s[78:79]
	s_add_i32 m0, s90, 0xe000
	s_nop 0
	global_load_lds_dwordx4 v[2:3], off
	s_waitcnt vmcnt(8)
	s_waitcnt lgkmcnt(0)
	s_barrier
	s_waitcnt lgkmcnt(0)
	v_mfma_f32_16x16x32_bf16 v[128:131], v[140:143], v[190:193], v[128:131]
	v_mfma_f32_16x16x32_bf16 v[124:127], v[148:151], v[190:193], v[124:127]
	v_mfma_f32_16x16x32_bf16 v[112:115], v[140:143], v[198:201], v[112:115]
	v_mfma_f32_16x16x32_bf16 v[108:111], v[148:151], v[198:201], v[108:111]
	v_mfma_f32_16x16x32_bf16 v[96:99], v[140:143], v[206:209], v[96:99]
	v_mfma_f32_16x16x32_bf16 v[92:95], v[148:151], v[206:209], v[92:95]
	v_mfma_f32_16x16x32_bf16 v[80:83], v[140:143], v[214:217], v[80:83]
	v_mfma_f32_16x16x32_bf16 v[76:79], v[148:151], v[214:217], v[76:79]
	v_mfma_f32_16x16x32_bf16 v[128:131], v[144:147], v[194:197], v[128:131]
	v_mfma_f32_16x16x32_bf16 v[124:127], v[166:169], v[194:197], v[124:127]
	v_mfma_f32_16x16x32_bf16 v[112:115], v[144:147], v[202:205], v[112:115]
	v_mfma_f32_16x16x32_bf16 v[108:111], v[166:169], v[202:205], v[108:111]
	v_mfma_f32_16x16x32_bf16 v[96:99], v[144:147], v[210:213], v[96:99]
	v_mfma_f32_16x16x32_bf16 v[92:95], v[166:169], v[210:213], v[92:95]
	v_mfma_f32_16x16x32_bf16 v[80:83], v[144:147], v[220:223], v[80:83]
	v_mfma_f32_16x16x32_bf16 v[76:79], v[166:169], v[220:223], v[76:79]
	v_mfma_f32_16x16x32_bf16 v[120:123], v[170:173], v[190:193], v[120:123]
	v_mfma_f32_16x16x32_bf16 v[116:119], v[178:181], v[190:193], v[116:119]
	v_mfma_f32_16x16x32_bf16 v[104:107], v[170:173], v[198:201], v[104:107]
	v_mfma_f32_16x16x32_bf16 v[100:103], v[178:181], v[198:201], v[100:103]
	v_mfma_f32_16x16x32_bf16 v[88:91], v[170:173], v[206:209], v[88:91]
	v_mfma_f32_16x16x32_bf16 v[84:87], v[178:181], v[206:209], v[84:87]
	v_mfma_f32_16x16x32_bf16 v[72:75], v[170:173], v[214:217], v[72:75]
	v_mfma_f32_16x16x32_bf16 v[68:71], v[178:181], v[214:217], v[68:71]
	v_mfma_f32_16x16x32_bf16 v[120:123], v[174:177], v[194:197], v[120:123]
	v_mfma_f32_16x16x32_bf16 v[116:119], v[182:185], v[194:197], v[116:119]
	v_mfma_f32_16x16x32_bf16 v[104:107], v[174:177], v[202:205], v[104:107]
	v_mfma_f32_16x16x32_bf16 v[100:103], v[182:185], v[202:205], v[100:103]
	v_mfma_f32_16x16x32_bf16 v[88:91], v[174:177], v[210:213], v[88:91]
	v_mfma_f32_16x16x32_bf16 v[84:87], v[182:185], v[210:213], v[84:87]
	v_mfma_f32_16x16x32_bf16 v[72:75], v[174:177], v[220:223], v[72:75]
	v_mfma_f32_16x16x32_bf16 v[68:71], v[182:185], v[220:223], v[68:71]
	s_barrier
	s_add_i32 s77, s15, s89
	v_lshl_add_u64 v[152:153], vcc, 0, v[132:133]
	s_mov_b32 m0, s77
	ds_read_b128 v[190:193], v161 offset:16384
	ds_read_b128 v[194:197], v161 offset:17408
	ds_read_b128 v[198:201], v161 offset:18432
	ds_read_b128 v[202:205], v161 offset:19456
	ds_read_b128 v[206:209], v161 offset:20480
	ds_read_b128 v[210:213], v161 offset:21504
	ds_read_b128 v[214:217], v161 offset:22528
	ds_read_b128 v[220:223], v161 offset:23552
	global_load_lds_dwordx4 v[152:153], off
	v_lshl_add_u64 v[2:3], v[152:153], 0, s[30:31]
	s_add_i32 m0, s77, 0x2000
	s_add_i32 s77, s18, s89
	global_load_lds_dwordx4 v[2:3], off
	v_lshl_add_u64 v[2:3], v[152:153], 0, s[34:35]
	s_mov_b32 m0, s77
	v_lshl_add_u64 v[186:187], s[8:9], 0, v[132:133]
	global_load_lds_dwordx4 v[2:3], off
	v_lshl_add_u64 v[2:3], v[152:153], 0, s[36:37]
	s_add_i32 m0, s77, 0x2000
	s_nop 0
	global_load_lds_dwordx4 v[2:3], off
	s_mov_b32 m0, s90
	v_lshl_add_u64 v[2:3], v[186:187], 0, s[30:31]
	global_load_lds_dwordx4 v[186:187], off
	s_mov_b32 m0, s91
	s_nop 0
	global_load_lds_dwordx4 v[2:3], off
	s_waitcnt vmcnt(8)
	s_waitcnt lgkmcnt(0)
	s_barrier
; #define PG8_STAGE(bufoff, gbase, voff) do { _Pragma("unroll") for (int _i = 0; _i < 2; ++_i) \
;         __builtin_amdgcn_global_load_lds((const unsigned*)((const char*)(gbase) + (voff)[_i]), (PG8_LAS unsigned*)(lds + (bufoff) + ldsw + _i * 8192), 16, 0, 0); } while (0)
; #define PG8_LDA(dst, b, h) do { _Pragma("unroll") for (int m = 0; m < 4; ++m) _Pragma("unroll") for (int k = 0; k < 2; ++k) dst[m][k] = *(const PG8_LAS bf16x8*)(lds + PG8_SA(b, h) + aoff + m * 2048 + k * 1024); } while (0)
; #define PG8_LDB(dst, b, h) do { _Pragma("unroll") for (int n = 0; n < 2; ++n) _Pragma("unroll") for (int k = 0; k < 2; ++k) dst[n][k] = *(const PG8_LAS bf16x8*)(lds + PG8_SB(b, h) + boff + n * 2048 + k * 1024); } while (0)
; #define PG8_MMA(ai, bj, At, Bt) do { __builtin_amdgcn_s_setprio(1); _Pragma("unroll") for (int m = 0; m < 4; ++m) _Pragma("unroll") for (int n = 0; n < 2; ++n) _Pragma("unroll") for (int k = 0; k < 2; ++k) \
;         acc[ai][bj][m][n] = __builtin_amdgcn_mfma_f32_16x16x32_bf16(Bt[n][k], At[m][k], acc[ai][bj][m][n], 0, 0, 0); __builtin_amdgcn_s_setprio(0); } while (0)
; #define PG8_WAIT_V(n) asm volatile("s_waitcnt vmcnt(" #n ")" ::: "memory")
; #define PG8_WAIT_L(n) asm volatile("s_waitcnt lgkmcnt(" #n ")" ::: "memory")
; #define PG8_BAR __builtin_amdgcn_s_barrier()
; #define PG8_SCHED __builtin_amdgcn_sched_barrier(0)
; template <class Epi, class Sched, bool ALIGN_EPI = false, bool SP2 = false>
; __device__ __forceinline__ void gemm_phase(PG8_LAS unsigned char* lds, const Gemm g, const Sched& S, const Epi& E) {
;     ...
;             PG8_WAIT_V(8); PG8_WAIT_L(0); PG8_BAR; PG8_MMA(1, 0, At, B0); PG8_MMA(1, 1, At, B1); PG8_BAR; PG8_SCHED;
;             PG8_LDB(B0, 1, 0); PG8_LDB(B1, 1, 1); PG8_SCHED; PG8_LDA(At, 1, 0); PG8_STAGE(PG8_SA(0, 1), a2 + hstepA, voffA);
;             PG8_WAIT_V(8); PG8_WAIT_L(0); PG8_BAR; PG8_MMA(0, 0, At, B0); PG8_MMA(0, 1, At, B1); PG8_BAR; PG8_SCHED;
	s_waitcnt lgkmcnt(0)
	v_mfma_f32_16x16x32_bf16 v[64:67], v[140:143], v[190:193], v[64:67]
	v_mfma_f32_16x16x32_bf16 v[60:63], v[148:151], v[190:193], v[60:63]
	v_mfma_f32_16x16x32_bf16 v[48:51], v[140:143], v[198:201], v[48:51]
	v_mfma_f32_16x16x32_bf16 v[44:47], v[148:151], v[198:201], v[44:47]
	v_mfma_f32_16x16x32_bf16 v[32:35], v[140:143], v[206:209], v[32:35]
	v_mfma_f32_16x16x32_bf16 v[28:31], v[148:151], v[206:209], v[28:31]
	v_mfma_f32_16x16x32_bf16 v[16:19], v[140:143], v[214:217], v[16:19]
	v_mfma_f32_16x16x32_bf16 v[12:15], v[148:151], v[214:217], v[12:15]
	v_mfma_f32_16x16x32_bf16 v[64:67], v[144:147], v[194:197], v[64:67]
	v_mfma_f32_16x16x32_bf16 v[60:63], v[166:169], v[194:197], v[60:63]
	v_mfma_f32_16x16x32_bf16 v[48:51], v[144:147], v[202:205], v[48:51]
	v_mfma_f32_16x16x32_bf16 v[44:47], v[166:169], v[202:205], v[44:47]
	v_mfma_f32_16x16x32_bf16 v[32:35], v[144:147], v[210:213], v[32:35]
	v_mfma_f32_16x16x32_bf16 v[28:31], v[166:169], v[210:213], v[28:31]
	v_mfma_f32_16x16x32_bf16 v[16:19], v[144:147], v[220:223], v[16:19]
	v_mfma_f32_16x16x32_bf16 v[12:15], v[166:169], v[220:223], v[12:15]
	v_mfma_f32_16x16x32_bf16 v[56:59], v[170:173], v[190:193], v[56:59]
	v_mfma_f32_16x16x32_bf16 v[52:55], v[178:181], v[190:193], v[52:55]
	v_mfma_f32_16x16x32_bf16 v[40:43], v[170:173], v[198:201], v[40:43]
	v_mfma_f32_16x16x32_bf16 v[36:39], v[178:181], v[198:201], v[36:39]
	v_mfma_f32_16x16x32_bf16 v[24:27], v[170:173], v[206:209], v[24:27]
	v_mfma_f32_16x16x32_bf16 v[20:23], v[178:181], v[206:209], v[20:23]
	v_mfma_f32_16x16x32_bf16 v[8:11], v[170:173], v[214:217], v[8:11]
	v_mfma_f32_16x16x32_bf16 v[2:5], v[178:181], v[214:217], v[4:7]
	v_mfma_f32_16x16x32_bf16 v[56:59], v[174:177], v[194:197], v[56:59]
	v_mfma_f32_16x16x32_bf16 v[52:55], v[182:185], v[194:197], v[52:55]
	v_mfma_f32_16x16x32_bf16 v[40:43], v[174:177], v[202:205], v[40:43]
	v_mfma_f32_16x16x32_bf16 v[36:39], v[182:185], v[202:205], v[36:39]
	v_mfma_f32_16x16x32_bf16 v[24:27], v[174:177], v[210:213], v[24:27]
	v_mfma_f32_16x16x32_bf16 v[20:23], v[182:185], v[210:213], v[20:23]
	v_mfma_f32_16x16x32_bf16 v[8:11], v[174:177], v[220:223], v[8:11]
	v_mfma_f32_16x16x32_bf16 v[2:5], v[182:185], v[220:223], v[2:5]
	s_barrier
	ds_read_b128 v[140:143], v162
	ds_read_b128 v[144:147], v162 offset:1024
	ds_read_b128 v[148:151], v162 offset:2048
	ds_read_b128 v[166:169], v162 offset:3072
	ds_read_b128 v[170:173], v163
	ds_read_b128 v[174:177], v163 offset:1024
	ds_read_b128 v[178:181], v163 offset:2048
	ds_read_b128 v[182:185], v163 offset:3072
	s_mov_b32 m0, s92
	v_lshl_add_u64 v[6:7], v[186:187], 0, s[34:35]
	ds_read_b128 v[190:193], v161 offset:32768
	ds_read_b128 v[194:197], v161 offset:33792
	ds_read_b128 v[198:201], v161 offset:34816
	ds_read_b128 v[202:205], v161 offset:35840
	ds_read_b128 v[206:209], v161 offset:36864
	ds_read_b128 v[210:213], v161 offset:37888
	ds_read_b128 v[214:217], v161 offset:38912
	ds_read_b128 v[220:223], v161 offset:39936
	global_load_lds_dwordx4 v[6:7], off
	v_lshl_add_u64 v[6:7], v[186:187], 0, s[36:37]
	s_mov_b32 m0, s93
	s_nop 0
	global_load_lds_dwordx4 v[6:7], off
	s_waitcnt vmcnt(8)
	s_waitcnt lgkmcnt(0)
	s_barrier
	s_waitcnt lgkmcnt(0)
	v_mfma_f32_16x16x32_bf16 v[128:131], v[140:143], v[190:193], v[128:131]
	v_mfma_f32_16x16x32_bf16 v[124:127], v[148:151], v[190:193], v[124:127]
	v_mfma_f32_16x16x32_bf16 v[112:115], v[140:143], v[198:201], v[112:115]
	v_mfma_f32_16x16x32_bf16 v[108:111], v[148:151], v[198:201], v[108:111]
	v_mfma_f32_16x16x32_bf16 v[96:99], v[140:143], v[206:209], v[96:99]
	v_mfma_f32_16x16x32_bf16 v[92:95], v[148:151], v[206:209], v[92:95]
	v_mfma_f32_16x16x32_bf16 v[80:83], v[140:143], v[214:217], v[80:83]
	v_mfma_f32_16x16x32_bf16 v[76:79], v[148:151], v[214:217], v[76:79]
	v_mfma_f32_16x16x32_bf16 v[128:131], v[144:147], v[194:197], v[128:131]
	v_mfma_f32_16x16x32_bf16 v[124:127], v[166:169], v[194:197], v[124:127]
	v_mfma_f32_16x16x32_bf16 v[112:115], v[144:147], v[202:205], v[112:115]
	v_mfma_f32_16x16x32_bf16 v[108:111], v[166:169], v[202:205], v[108:111]
	v_mfma_f32_16x16x32_bf16 v[96:99], v[144:147], v[210:213], v[96:99]
	v_mfma_f32_16x16x32_bf16 v[92:95], v[166:169], v[210:213], v[92:95]
	v_mfma_f32_16x16x32_bf16 v[80:83], v[144:147], v[220:223], v[80:83]
	v_mfma_f32_16x16x32_bf16 v[76:79], v[166:169], v[220:223], v[76:79]
	v_mfma_f32_16x16x32_bf16 v[120:123], v[170:173], v[190:193], v[120:123]
	v_mfma_f32_16x16x32_bf16 v[116:119], v[178:181], v[190:193], v[116:119]
	v_mfma_f32_16x16x32_bf16 v[104:107], v[170:173], v[198:201], v[104:107]
	v_mfma_f32_16x16x32_bf16 v[100:103], v[178:181], v[198:201], v[100:103]
	v_mfma_f32_16x16x32_bf16 v[88:91], v[170:173], v[206:209], v[88:91]
	v_mfma_f32_16x16x32_bf16 v[84:87], v[178:181], v[206:209], v[84:87]
	v_mfma_f32_16x16x32_bf16 v[72:75], v[170:173], v[214:217], v[72:75]
	v_mfma_f32_16x16x32_bf16 v[68:71], v[178:181], v[214:217], v[68:71]
	v_mfma_f32_16x16x32_bf16 v[120:123], v[174:177], v[194:197], v[120:123]
	v_mfma_f32_16x16x32_bf16 v[116:119], v[182:185], v[194:197], v[116:119]
	v_mfma_f32_16x16x32_bf16 v[104:107], v[174:177], v[202:205], v[104:107]
	v_mfma_f32_16x16x32_bf16 v[100:103], v[182:185], v[202:205], v[100:103]
	v_mfma_f32_16x16x32_bf16 v[88:91], v[174:177], v[210:213], v[88:91]
	v_mfma_f32_16x16x32_bf16 v[84:87], v[182:185], v[210:213], v[84:87]
	v_mfma_f32_16x16x32_bf16 v[72:75], v[174:177], v[220:223], v[72:75]
	v_mfma_f32_16x16x32_bf16 v[68:71], v[182:185], v[220:223], v[68:71]
	s_barrier
; #define PG8_STAGE(bufoff, gbase, voff) do { _Pragma("unroll") for (int _i = 0; _i < 2; ++_i) \
;         __builtin_amdgcn_global_load_lds((const unsigned*)((const char*)(gbase) + (voff)[_i]), (PG8_LAS unsigned*)(lds + (bufoff) + ldsw + _i * 8192), 16, 0, 0); } while (0)
; #define PG8_LDA(dst, b, h) do { _Pragma("unroll") for (int m = 0; m < 4; ++m) _Pragma("unroll") for (int k = 0; k < 2; ++k) dst[m][k] = *(const PG8_LAS bf16x8*)(lds + PG8_SA(b, h) + aoff + m * 2048 + k * 1024); } while (0)
; #define PG8_MMA(ai, bj, At, Bt) do { __builtin_amdgcn_s_setprio(1); _Pragma("unroll") for (int m = 0; m < 4; ++m) _Pragma("unroll") for (int n = 0; n < 2; ++n) _Pragma("unroll") for (int k = 0; k < 2; ++k) \
;         acc[ai][bj][m][n] = __builtin_amdgcn_mfma_f32_16x16x32_bf16(Bt[n][k], At[m][k], acc[ai][bj][m][n], 0, 0, 0); __builtin_amdgcn_s_setprio(0); } while (0)
; #define PG8_WAIT_V(n) asm volatile("s_waitcnt vmcnt(" #n ")" ::: "memory")
; #define PG8_WAIT_L(n) asm volatile("s_waitcnt lgkmcnt(" #n ")" ::: "memory")
; #define PG8_BAR __builtin_amdgcn_s_barrier()
; #define PG8_SCHED __builtin_amdgcn_sched_barrier(0)
; template <class Epi, class Sched, bool ALIGN_EPI = false, bool SP2 = false>
; __device__ __forceinline__ void gemm_phase(PG8_LAS unsigned char* lds, const Gemm g, const Sched& S, const Epi& E) {
;     ...
;             PG8_LDA(At, 1, 1); PG8_STAGE(PG8_SB(1, 0), b3, voffB); PG8_STAGE(PG8_SB(1, 1), b3 + hstepB, voffB); PG8_STAGE(PG8_SA(1, 0), a3, voffA);
;             PG8_WAIT_V(8); PG8_WAIT_L(0); PG8_BAR; PG8_MMA(1, 0, At, B0); PG8_MMA(1, 1, At, B1); PG8_BAR; PG8_SCHED;
	s_add_i32 s8, s19, s89
	v_lshl_add_u64 v[6:7], v[152:153], 0, s[38:39]
	s_mov_b32 m0, s8
	ds_read_b128 v[190:193], v161 offset:49152
	ds_read_b128 v[194:197], v161 offset:50176
	ds_read_b128 v[198:201], v161 offset:51200
	ds_read_b128 v[202:205], v161 offset:52224
	ds_read_b128 v[206:209], v161 offset:53248
	ds_read_b128 v[210:213], v161 offset:54272
	ds_read_b128 v[214:217], v161 offset:55296
	ds_read_b128 v[220:223], v161 offset:56320
	global_load_lds_dwordx4 v[6:7], off
	v_lshl_add_u64 v[6:7], v[152:153], 0, s[40:41]
	s_add_i32 m0, s8, 0x2000
	s_add_i32 s8, s80, s89
	global_load_lds_dwordx4 v[6:7], off
	v_lshl_add_u64 v[6:7], v[152:153], 0, s[52:53]
	s_mov_b32 m0, s8
	s_nop 0
	global_load_lds_dwordx4 v[6:7], off
	v_lshl_add_u64 v[6:7], v[152:153], 0, s[54:55]
	s_add_i32 m0, s8, 0x2000
	s_nop 0
	global_load_lds_dwordx4 v[6:7], off
	v_lshl_add_u64 v[6:7], v[186:187], 0, s[38:39]
	s_mov_b32 m0, s94
	s_nop 0
	global_load_lds_dwordx4 v[6:7], off
	v_lshl_add_u64 v[6:7], v[186:187], 0, s[40:41]
	s_mov_b32 m0, s95
	s_nop 0
	global_load_lds_dwordx4 v[6:7], off
	s_waitcnt vmcnt(8)
	s_waitcnt lgkmcnt(0)
	s_barrier
	s_waitcnt lgkmcnt(0)
	v_mfma_f32_16x16x32_bf16 v[64:67], v[140:143], v[190:193], v[64:67]
	v_mfma_f32_16x16x32_bf16 v[60:63], v[148:151], v[190:193], v[60:63]
	v_mfma_f32_16x16x32_bf16 v[48:51], v[140:143], v[198:201], v[48:51]
	v_mfma_f32_16x16x32_bf16 v[44:47], v[148:151], v[198:201], v[44:47]
	v_mfma_f32_16x16x32_bf16 v[32:35], v[140:143], v[206:209], v[32:35]
	v_mfma_f32_16x16x32_bf16 v[28:31], v[148:151], v[206:209], v[28:31]
	v_mfma_f32_16x16x32_bf16 v[16:19], v[140:143], v[214:217], v[16:19]
	v_mfma_f32_16x16x32_bf16 v[12:15], v[148:151], v[214:217], v[12:15]
	v_mfma_f32_16x16x32_bf16 v[64:67], v[144:147], v[194:197], v[64:67]
	v_mfma_f32_16x16x32_bf16 v[60:63], v[166:169], v[194:197], v[60:63]
	v_mfma_f32_16x16x32_bf16 v[48:51], v[144:147], v[202:205], v[48:51]
	v_mfma_f32_16x16x32_bf16 v[44:47], v[166:169], v[202:205], v[44:47]
	v_mfma_f32_16x16x32_bf16 v[32:35], v[144:147], v[210:213], v[32:35]
	v_mfma_f32_16x16x32_bf16 v[28:31], v[166:169], v[210:213], v[28:31]
	v_mfma_f32_16x16x32_bf16 v[16:19], v[144:147], v[220:223], v[16:19]
	v_mfma_f32_16x16x32_bf16 v[12:15], v[166:169], v[220:223], v[12:15]
	v_mfma_f32_16x16x32_bf16 v[56:59], v[170:173], v[190:193], v[56:59]
	v_mfma_f32_16x16x32_bf16 v[52:55], v[178:181], v[190:193], v[52:55]
	v_mfma_f32_16x16x32_bf16 v[40:43], v[170:173], v[198:201], v[40:43]
	v_mfma_f32_16x16x32_bf16 v[36:39], v[178:181], v[198:201], v[36:39]
	v_mfma_f32_16x16x32_bf16 v[24:27], v[170:173], v[206:209], v[24:27]
	v_mfma_f32_16x16x32_bf16 v[20:23], v[178:181], v[206:209], v[20:23]
	v_mfma_f32_16x16x32_bf16 v[6:9], v[170:173], v[214:217], v[8:11]
	v_mfma_f32_16x16x32_bf16 v[2:5], v[178:181], v[214:217], v[2:5]
	v_mfma_f32_16x16x32_bf16 v[56:59], v[174:177], v[194:197], v[56:59]
	v_mfma_f32_16x16x32_bf16 v[52:55], v[182:185], v[194:197], v[52:55]
	v_mfma_f32_16x16x32_bf16 v[40:43], v[174:177], v[202:205], v[40:43]
	v_mfma_f32_16x16x32_bf16 v[36:39], v[182:185], v[202:205], v[36:39]
	v_mfma_f32_16x16x32_bf16 v[24:27], v[174:177], v[210:213], v[24:27]
	v_mfma_f32_16x16x32_bf16 v[20:23], v[182:185], v[210:213], v[20:23]
	v_mfma_f32_16x16x32_bf16 v[8:11], v[174:177], v[220:223], v[6:9]
	v_mfma_f32_16x16x32_bf16 v[4:7], v[182:185], v[220:223], v[2:5]
	s_barrier
	s_add_i32 s76, s76, 2
	s_add_u32 s4, s4, 0x10000
	s_addc_u32 s5, s5, 0
	s_add_u32 s74, s74, 0x10000
	s_addc_u32 s75, s75, 0
	s_cmp_gt_u32 s76, 13
	s_cbranch_scc0 .LBB0_315

; #define PG8_STAGE(bufoff, gbase, voff) do { _Pragma("unroll") for (int _i = 0; _i < 2; ++_i) \
;         __builtin_amdgcn_global_load_lds((const unsigned*)((const char*)(gbase) + (voff)[_i]), (PG8_LAS unsigned*)(lds + (bufoff) + ldsw + _i * 8192), 16, 0, 0); } while (0)
; #define PG8_LDA(dst, b, h) do { _Pragma("unroll") for (int m = 0; m < 4; ++m) _Pragma("unroll") for (int k = 0; k < 2; ++k) dst[m][k] = *(const PG8_LAS bf16x8*)(lds + PG8_SA(b, h) + aoff + m * 2048 + k * 1024); } while (0)
; #define PG8_LDB(dst, b, h) do { _Pragma("unroll") for (int n = 0; n < 2; ++n) _Pragma("unroll") for (int k = 0; k < 2; ++k) dst[n][k] = *(const PG8_LAS bf16x8*)(lds + PG8_SB(b, h) + boff + n * 2048 + k * 1024); } while (0)
; #define PG8_MMA(ai, bj, At, Bt) do { __builtin_amdgcn_s_setprio(1); _Pragma("unroll") for (int m = 0; m < 4; ++m) _Pragma("unroll") for (int n = 0; n < 2; ++n) _Pragma("unroll") for (int k = 0; k < 2; ++k) \
;         acc[ai][bj][m][n] = __builtin_amdgcn_mfma_f32_16x16x32_bf16(Bt[n][k], At[m][k], acc[ai][bj][m][n], 0, 0, 0); __builtin_amdgcn_s_setprio(0); } while (0)
; #define PG8_WAIT_V(n) asm volatile("s_waitcnt vmcnt(" #n ")" ::: "memory")
; #define PG8_WAIT_L(n) asm volatile("s_waitcnt lgkmcnt(" #n ")" ::: "memory")
; #define PG8_BAR __builtin_amdgcn_s_barrier()
; #define PG8_SCHED __builtin_amdgcn_sched_barrier(0)
; template <class Epi, class Sched, bool ALIGN_EPI = false, bool SP2 = false>
; __device__ __forceinline__ void gemm_phase(PG8_LAS unsigned char* lds, const Gemm g, const Sched& S, const Epi& E) {
;     ...
;         const bool has_next = S.next(ui + 1, nxt);
;         const char* nA = has_next ? (const char*)g.A + (size_t)nxt.pm * tstepA : cA; const char* nB = has_next ? (const char*)g.Bt + (size_t)nxt.pn * tstepB : cB;
;     ...
;             PG8_LDB(B0, 0, 0); PG8_LDB(B1, 0, 1); PG8_SCHED; PG8_LDA(At, 0, 0); PG8_STAGE(PG8_SA(1, 1), a1 + hstepA, voffA);
;             PG8_WAIT_V(8); PG8_WAIT_L(0); PG8_BAR; PG8_MMA(0, 0, At, B0); PG8_MMA(0, 1, At, B1); PG8_BAR; PG8_SCHED;
;             PG8_LDA(At, 0, 1); PG8_STAGE(PG8_SB(0, 0), b2, voffB); PG8_STAGE(PG8_SB(0, 1), b2 + hstepB, voffB); PG8_STAGE(PG8_SA(0, 0), a2, voffA);
;             PG8_WAIT_V(8); PG8_WAIT_L(0); PG8_BAR; PG8_MMA(1, 0, At, B0); PG8_MMA(1, 1, At, B1); PG8_BAR; PG8_SCHED;
.LBB0_744:
	s_add_u32 s68, s68, 0x10000
	s_addc_u32 s69, s69, 0
	s_add_u32 s70, s70, 0x10000
	s_addc_u32 s71, s71, 0
	s_mov_b32 s72, -2
	s_waitcnt lgkmcnt(0)
	ds_read_b128 v[128:131], v211
	ds_read_b128 v[132:135], v211 offset:1024
	ds_read_b128 v[136:139], v211 offset:2048
	ds_read_b128 v[140:143], v211 offset:3072
	ds_read_b128 v[144:147], v212
	ds_read_b128 v[148:151], v212 offset:1024
	ds_read_b128 v[152:155], v212 offset:2048
	ds_read_b128 v[156:159], v212 offset:3072
	s_cmp_eq_u32 s72, 12
	s_cselect_b32 s79, s59, s69
	s_cselect_b32 s78, s65, s68
	s_cselect_b32 s91, s57, s71
	s_cselect_b32 s90, s67, s70
	v_lshl_add_u64 v[208:209], s[68:69], 0, v[190:191]
	v_lshl_add_u64 v[228:229], v[208:209], 0, s[52:53]
	s_add_i32 m0, s15, 0xc000
	ds_read_b128 v[160:163], v213
	ds_read_b128 v[164:167], v213 offset:1024
	ds_read_b128 v[168:171], v213 offset:2048
	ds_read_b128 v[172:175], v213 offset:3072
	ds_read_b128 v[176:179], v213 offset:4096
	ds_read_b128 v[180:183], v213 offset:5120
	ds_read_b128 v[220:223], v213 offset:6144
	ds_read_b128 v[224:227], v213 offset:7168
	global_load_lds_dwordx4 v[228:229], off
	v_lshl_add_u64 v[208:209], v[208:209], 0, s[54:55]
	s_add_i32 m0, s15, 0xe000
	s_nop 0
	global_load_lds_dwordx4 v[208:209], off
	s_waitcnt vmcnt(8)
	s_waitcnt lgkmcnt(0)
	s_barrier
	s_waitcnt lgkmcnt(0)
	v_mfma_f32_16x16x32_bf16 v[124:127], v[128:131], v[160:163], 0
	v_mfma_f32_16x16x32_bf16 v[120:123], v[136:139], v[160:163], 0
	v_mfma_f32_16x16x32_bf16 v[108:111], v[128:131], v[168:171], 0
	v_mfma_f32_16x16x32_bf16 v[104:107], v[136:139], v[168:171], 0
	v_mfma_f32_16x16x32_bf16 v[92:95], v[128:131], v[176:179], 0
	v_mfma_f32_16x16x32_bf16 v[88:91], v[136:139], v[176:179], 0
	v_mfma_f32_16x16x32_bf16 v[76:79], v[128:131], v[220:223], 0
	v_mfma_f32_16x16x32_bf16 v[72:75], v[136:139], v[220:223], 0
	v_mfma_f32_16x16x32_bf16 v[124:127], v[132:135], v[164:167], v[124:127]
	v_mfma_f32_16x16x32_bf16 v[120:123], v[140:143], v[164:167], v[120:123]
	v_mfma_f32_16x16x32_bf16 v[108:111], v[132:135], v[172:175], v[108:111]
	v_mfma_f32_16x16x32_bf16 v[104:107], v[140:143], v[172:175], v[104:107]
	v_mfma_f32_16x16x32_bf16 v[92:95], v[132:135], v[180:183], v[92:95]
	v_mfma_f32_16x16x32_bf16 v[88:91], v[140:143], v[180:183], v[88:91]
	v_mfma_f32_16x16x32_bf16 v[76:79], v[132:135], v[224:227], v[76:79]
	v_mfma_f32_16x16x32_bf16 v[72:75], v[140:143], v[224:227], v[72:75]
	v_mfma_f32_16x16x32_bf16 v[116:119], v[144:147], v[160:163], 0
	v_mfma_f32_16x16x32_bf16 v[112:115], v[152:155], v[160:163], 0
	v_mfma_f32_16x16x32_bf16 v[100:103], v[144:147], v[168:171], 0
	v_mfma_f32_16x16x32_bf16 v[96:99], v[152:155], v[168:171], 0
	v_mfma_f32_16x16x32_bf16 v[84:87], v[144:147], v[176:179], 0
	v_mfma_f32_16x16x32_bf16 v[80:83], v[152:155], v[176:179], 0
	v_mfma_f32_16x16x32_bf16 v[68:71], v[144:147], v[220:223], 0
	v_mfma_f32_16x16x32_bf16 v[64:67], v[152:155], v[220:223], 0
	v_mfma_f32_16x16x32_bf16 v[116:119], v[148:151], v[164:167], v[116:119]
	v_mfma_f32_16x16x32_bf16 v[112:115], v[156:159], v[164:167], v[112:115]
	v_mfma_f32_16x16x32_bf16 v[100:103], v[148:151], v[172:175], v[100:103]
	v_mfma_f32_16x16x32_bf16 v[96:99], v[156:159], v[172:175], v[96:99]
	v_mfma_f32_16x16x32_bf16 v[84:87], v[148:151], v[180:183], v[84:87]
	v_mfma_f32_16x16x32_bf16 v[80:83], v[156:159], v[180:183], v[80:83]
	v_mfma_f32_16x16x32_bf16 v[68:71], v[148:151], v[224:227], v[68:71]
	v_mfma_f32_16x16x32_bf16 v[64:67], v[156:159], v[224:227], v[64:67]
	s_barrier
	s_add_i32 s73, s85, s14
	v_lshl_add_u64 v[208:209], s[90:91], 0, v[190:191]
	s_mov_b32 m0, s73
	ds_read_b128 v[160:163], v213 offset:16384
	ds_read_b128 v[164:167], v213 offset:17408
	ds_read_b128 v[168:171], v213 offset:18432
	ds_read_b128 v[172:175], v213 offset:19456
	ds_read_b128 v[176:179], v213 offset:20480
	ds_read_b128 v[180:183], v213 offset:21504
	ds_read_b128 v[220:223], v213 offset:22528
	ds_read_b128 v[224:227], v213 offset:23552
	global_load_lds_dwordx4 v[208:209], off
	v_lshl_add_u64 v[228:229], v[208:209], 0, s[10:11]
	s_add_i32 m0, s73, 0x2000
	s_add_i32 s73, s86, s14
	global_load_lds_dwordx4 v[228:229], off
	v_lshl_add_u64 v[228:229], v[208:209], 0, s[34:35]
	s_mov_b32 m0, s73
	s_nop 0
	global_load_lds_dwordx4 v[228:229], off
	v_lshl_add_u64 v[228:229], v[208:209], 0, s[36:37]
	s_add_i32 m0, s73, 0x2000
	s_nop 0
	global_load_lds_dwordx4 v[228:229], off
	v_lshl_add_u64 v[228:229], s[78:79], 0, v[190:191]
	s_mov_b32 m0, s15
	v_lshl_add_u64 v[230:231], v[228:229], 0, s[10:11]
	global_load_lds_dwordx4 v[228:229], off
	s_mov_b32 m0, s17
	s_nop 0
	global_load_lds_dwordx4 v[230:231], off
	s_waitcnt vmcnt(8)
	s_waitcnt lgkmcnt(0)
	s_barrier
; #define PG8_STAGE(bufoff, gbase, voff) do { _Pragma("unroll") for (int _i = 0; _i < 2; ++_i) \
;         __builtin_amdgcn_global_load_lds((const unsigned*)((const char*)(gbase) + (voff)[_i]), (PG8_LAS unsigned*)(lds + (bufoff) + ldsw + _i * 8192), 16, 0, 0); } while (0)
; #define PG8_LDA(dst, b, h) do { _Pragma("unroll") for (int m = 0; m < 4; ++m) _Pragma("unroll") for (int k = 0; k < 2; ++k) dst[m][k] = *(const PG8_LAS bf16x8*)(lds + PG8_SA(b, h) + aoff + m * 2048 + k * 1024); } while (0)
; #define PG8_LDB(dst, b, h) do { _Pragma("unroll") for (int n = 0; n < 2; ++n) _Pragma("unroll") for (int k = 0; k < 2; ++k) dst[n][k] = *(const PG8_LAS bf16x8*)(lds + PG8_SB(b, h) + boff + n * 2048 + k * 1024); } while (0)
; #define PG8_MMA(ai, bj, At, Bt) do { __builtin_amdgcn_s_setprio(1); _Pragma("unroll") for (int m = 0; m < 4; ++m) _Pragma("unroll") for (int n = 0; n < 2; ++n) _Pragma("unroll") for (int k = 0; k < 2; ++k) \
;         acc[ai][bj][m][n] = __builtin_amdgcn_mfma_f32_16x16x32_bf16(Bt[n][k], At[m][k], acc[ai][bj][m][n], 0, 0, 0); __builtin_amdgcn_s_setprio(0); } while (0)
; #define PG8_WAIT_V(n) asm volatile("s_waitcnt vmcnt(" #n ")" ::: "memory")
; #define PG8_WAIT_L(n) asm volatile("s_waitcnt lgkmcnt(" #n ")" ::: "memory")
; #define PG8_BAR __builtin_amdgcn_s_barrier()
; #define PG8_SCHED __builtin_amdgcn_sched_barrier(0)
; template <class Epi, class Sched, bool ALIGN_EPI = false, bool SP2 = false>
; __device__ __forceinline__ void gemm_phase(PG8_LAS unsigned char* lds, const Gemm g, const Sched& S, const Epi& E) {
;     ...
;             PG8_WAIT_V(8); PG8_WAIT_L(0); PG8_BAR; PG8_MMA(1, 0, At, B0); PG8_MMA(1, 1, At, B1); PG8_BAR; PG8_SCHED;
;             PG8_LDB(B0, 1, 0); PG8_LDB(B1, 1, 1); PG8_SCHED; PG8_LDA(At, 1, 0); PG8_STAGE(PG8_SA(0, 1), a2 + hstepA, voffA);
;             PG8_WAIT_V(8); PG8_WAIT_L(0); PG8_BAR; PG8_MMA(0, 0, At, B0); PG8_MMA(0, 1, At, B1); PG8_BAR; PG8_SCHED;
	s_waitcnt lgkmcnt(0)
	v_mfma_f32_16x16x32_bf16 v[60:63], v[128:131], v[160:163], 0
	v_mfma_f32_16x16x32_bf16 v[56:59], v[136:139], v[160:163], 0
	v_mfma_f32_16x16x32_bf16 v[44:47], v[128:131], v[168:171], 0
	v_mfma_f32_16x16x32_bf16 v[40:43], v[136:139], v[168:171], 0
	v_mfma_f32_16x16x32_bf16 v[28:31], v[128:131], v[176:179], 0
	v_mfma_f32_16x16x32_bf16 v[24:27], v[136:139], v[176:179], 0
	v_mfma_f32_16x16x32_bf16 v[12:15], v[128:131], v[220:223], 0
	v_mfma_f32_16x16x32_bf16 v[8:11], v[136:139], v[220:223], 0
	v_mfma_f32_16x16x32_bf16 v[60:63], v[132:135], v[164:167], v[60:63]
	v_mfma_f32_16x16x32_bf16 v[56:59], v[140:143], v[164:167], v[56:59]
	v_mfma_f32_16x16x32_bf16 v[44:47], v[132:135], v[172:175], v[44:47]
	v_mfma_f32_16x16x32_bf16 v[40:43], v[140:143], v[172:175], v[40:43]
	v_mfma_f32_16x16x32_bf16 v[28:31], v[132:135], v[180:183], v[28:31]
	v_mfma_f32_16x16x32_bf16 v[24:27], v[140:143], v[180:183], v[24:27]
	v_mfma_f32_16x16x32_bf16 v[12:15], v[132:135], v[224:227], v[12:15]
	v_mfma_f32_16x16x32_bf16 v[8:11], v[140:143], v[224:227], v[8:11]
	v_mfma_f32_16x16x32_bf16 v[52:55], v[144:147], v[160:163], 0
	v_mfma_f32_16x16x32_bf16 v[48:51], v[152:155], v[160:163], 0
	v_mfma_f32_16x16x32_bf16 v[36:39], v[144:147], v[168:171], 0
	v_mfma_f32_16x16x32_bf16 v[32:35], v[152:155], v[168:171], 0
	v_mfma_f32_16x16x32_bf16 v[20:23], v[144:147], v[176:179], 0
	v_mfma_f32_16x16x32_bf16 v[16:19], v[152:155], v[176:179], 0
	v_mfma_f32_16x16x32_bf16 v[4:7], v[144:147], v[220:223], 0
	v_mfma_f32_16x16x32_bf16 v[0:3], v[152:155], v[220:223], 0
	v_mfma_f32_16x16x32_bf16 v[52:55], v[148:151], v[164:167], v[52:55]
	v_mfma_f32_16x16x32_bf16 v[48:51], v[156:159], v[164:167], v[48:51]
	v_mfma_f32_16x16x32_bf16 v[36:39], v[148:151], v[172:175], v[36:39]
	v_mfma_f32_16x16x32_bf16 v[32:35], v[156:159], v[172:175], v[32:35]
	v_mfma_f32_16x16x32_bf16 v[20:23], v[148:151], v[180:183], v[20:23]
	v_mfma_f32_16x16x32_bf16 v[16:19], v[156:159], v[180:183], v[16:19]
	v_mfma_f32_16x16x32_bf16 v[4:7], v[148:151], v[224:227], v[4:7]
	v_mfma_f32_16x16x32_bf16 v[0:3], v[156:159], v[224:227], v[0:3]
	s_barrier
	ds_read_b128 v[128:131], v214
	ds_read_b128 v[132:135], v214 offset:1024
	ds_read_b128 v[136:139], v214 offset:2048
	ds_read_b128 v[140:143], v214 offset:3072
	ds_read_b128 v[144:147], v215
	ds_read_b128 v[148:151], v215 offset:1024
	ds_read_b128 v[152:155], v215 offset:2048
	ds_read_b128 v[156:159], v215 offset:3072
	s_mov_b32 m0, s18
	v_lshl_add_u64 v[230:231], v[228:229], 0, s[34:35]
	ds_read_b128 v[160:163], v213 offset:32768
	ds_read_b128 v[164:167], v213 offset:33792
	ds_read_b128 v[168:171], v213 offset:34816
	ds_read_b128 v[172:175], v213 offset:35840
	ds_read_b128 v[176:179], v213 offset:36864
	ds_read_b128 v[180:183], v213 offset:37888
	ds_read_b128 v[220:223], v213 offset:38912
	ds_read_b128 v[224:227], v213 offset:39936
	global_load_lds_dwordx4 v[230:231], off
	v_lshl_add_u64 v[230:231], v[228:229], 0, s[36:37]
	s_mov_b32 m0, s19
	s_nop 0
	global_load_lds_dwordx4 v[230:231], off
	s_waitcnt vmcnt(8)
	s_waitcnt lgkmcnt(0)
	s_barrier
	s_waitcnt lgkmcnt(0)
	v_mfma_f32_16x16x32_bf16 v[124:127], v[128:131], v[160:163], v[124:127]
	v_mfma_f32_16x16x32_bf16 v[120:123], v[136:139], v[160:163], v[120:123]
	v_mfma_f32_16x16x32_bf16 v[108:111], v[128:131], v[168:171], v[108:111]
	v_mfma_f32_16x16x32_bf16 v[104:107], v[136:139], v[168:171], v[104:107]
	v_mfma_f32_16x16x32_bf16 v[92:95], v[128:131], v[176:179], v[92:95]
	v_mfma_f32_16x16x32_bf16 v[88:91], v[136:139], v[176:179], v[88:91]
	v_mfma_f32_16x16x32_bf16 v[76:79], v[128:131], v[220:223], v[76:79]
	v_mfma_f32_16x16x32_bf16 v[72:75], v[136:139], v[220:223], v[72:75]
	v_mfma_f32_16x16x32_bf16 v[124:127], v[132:135], v[164:167], v[124:127]
	v_mfma_f32_16x16x32_bf16 v[120:123], v[140:143], v[164:167], v[120:123]
	v_mfma_f32_16x16x32_bf16 v[108:111], v[132:135], v[172:175], v[108:111]
	v_mfma_f32_16x16x32_bf16 v[104:107], v[140:143], v[172:175], v[104:107]
	v_mfma_f32_16x16x32_bf16 v[92:95], v[132:135], v[180:183], v[92:95]
	v_mfma_f32_16x16x32_bf16 v[88:91], v[140:143], v[180:183], v[88:91]
	v_mfma_f32_16x16x32_bf16 v[76:79], v[132:135], v[224:227], v[76:79]
	v_mfma_f32_16x16x32_bf16 v[72:75], v[140:143], v[224:227], v[72:75]
	v_mfma_f32_16x16x32_bf16 v[116:119], v[144:147], v[160:163], v[116:119]
	v_mfma_f32_16x16x32_bf16 v[112:115], v[152:155], v[160:163], v[112:115]
	v_mfma_f32_16x16x32_bf16 v[100:103], v[144:147], v[168:171], v[100:103]
	v_mfma_f32_16x16x32_bf16 v[96:99], v[152:155], v[168:171], v[96:99]
	v_mfma_f32_16x16x32_bf16 v[84:87], v[144:147], v[176:179], v[84:87]
	v_mfma_f32_16x16x32_bf16 v[80:83], v[152:155], v[176:179], v[80:83]
	v_mfma_f32_16x16x32_bf16 v[68:71], v[144:147], v[220:223], v[68:71]
	v_mfma_f32_16x16x32_bf16 v[64:67], v[152:155], v[220:223], v[64:67]
	v_mfma_f32_16x16x32_bf16 v[116:119], v[148:151], v[164:167], v[116:119]
	v_mfma_f32_16x16x32_bf16 v[112:115], v[156:159], v[164:167], v[112:115]
	v_mfma_f32_16x16x32_bf16 v[100:103], v[148:151], v[172:175], v[100:103]
	v_mfma_f32_16x16x32_bf16 v[96:99], v[156:159], v[172:175], v[96:99]
	v_mfma_f32_16x16x32_bf16 v[84:87], v[148:151], v[180:183], v[84:87]
	v_mfma_f32_16x16x32_bf16 v[80:83], v[156:159], v[180:183], v[80:83]
	v_mfma_f32_16x16x32_bf16 v[68:71], v[148:151], v[224:227], v[68:71]
	v_mfma_f32_16x16x32_bf16 v[64:67], v[156:159], v[224:227], v[64:67]
	s_barrier
; #define PG8_STAGE(bufoff, gbase, voff) do { _Pragma("unroll") for (int _i = 0; _i < 2; ++_i) \
;         __builtin_amdgcn_global_load_lds((const unsigned*)((const char*)(gbase) + (voff)[_i]), (PG8_LAS unsigned*)(lds + (bufoff) + ldsw + _i * 8192), 16, 0, 0); } while (0)
; #define PG8_LDA(dst, b, h) do { _Pragma("unroll") for (int m = 0; m < 4; ++m) _Pragma("unroll") for (int k = 0; k < 2; ++k) dst[m][k] = *(const PG8_LAS bf16x8*)(lds + PG8_SA(b, h) + aoff + m * 2048 + k * 1024); } while (0)
; #define PG8_MMA(ai, bj, At, Bt) do { __builtin_amdgcn_s_setprio(1); _Pragma("unroll") for (int m = 0; m < 4; ++m) _Pragma("unroll") for (int n = 0; n < 2; ++n) _Pragma("unroll") for (int k = 0; k < 2; ++k) \
;         acc[ai][bj][m][n] = __builtin_amdgcn_mfma_f32_16x16x32_bf16(Bt[n][k], At[m][k], acc[ai][bj][m][n], 0, 0, 0); __builtin_amdgcn_s_setprio(0); } while (0)
; #define PG8_WAIT_V(n) asm volatile("s_waitcnt vmcnt(" #n ")" ::: "memory")
; #define PG8_WAIT_L(n) asm volatile("s_waitcnt lgkmcnt(" #n ")" ::: "memory")
; #define PG8_BAR __builtin_amdgcn_s_barrier()
; #define PG8_SCHED __builtin_amdgcn_sched_barrier(0)
;     __host__ __device__ bool next(int i, Unit& u) const {
;         const long L = (long)i * G + c; if (L >= nwg) return false;
;         int wgid = (int)L; { const int q = nwg / NXCD, r = nwg % NXCD, xcd = wgid % NXCD, off = wgid / NXCD; wgid = (xcd < r ? xcd * (q + 1) : r * (q + 1) + (xcd - r) * q) + off; }
;         const int nig = wgm * nN, gid = wgid / nig, fm = gid * wgm, gsz = (nM - fm) < wgm ? (nM - fm) : wgm;
;         u.pm = fm + ((wgid % nig) % gsz); u.pn = (wgid % nig) / gsz; return true;
; template <class Epi, class Sched, bool ALIGN_EPI = false, bool SP2 = false>
; __device__ __forceinline__ void gemm_phase(PG8_LAS unsigned char* lds, const Gemm g, const Sched& S, const Epi& E) {
;     ...
;             PG8_LDA(At, 1, 1); PG8_STAGE(PG8_SB(1, 0), b3, voffB); PG8_STAGE(PG8_SB(1, 1), b3 + hstepB, voffB); PG8_STAGE(PG8_SA(1, 0), a3, voffA);
;             PG8_WAIT_V(8); PG8_WAIT_L(0); PG8_BAR; PG8_MMA(1, 0, At, B0); PG8_MMA(1, 1, At, B1); PG8_BAR; PG8_SCHED;
	s_add_i32 s73, s87, s14
	v_lshl_add_u64 v[230:231], v[208:209], 0, s[38:39]
	s_mov_b32 m0, s73
	ds_read_b128 v[160:163], v213 offset:49152
	ds_read_b128 v[164:167], v213 offset:50176
	ds_read_b128 v[168:171], v213 offset:51200
	ds_read_b128 v[172:175], v213 offset:52224
	ds_read_b128 v[176:179], v213 offset:53248
	ds_read_b128 v[180:183], v213 offset:54272
	ds_read_b128 v[220:223], v213 offset:55296
	ds_read_b128 v[224:227], v213 offset:56320
	global_load_lds_dwordx4 v[230:231], off
	v_lshl_add_u64 v[230:231], v[208:209], 0, s[40:41]
	s_add_i32 m0, s73, 0x2000
	s_add_i32 s73, s88, s14
	global_load_lds_dwordx4 v[230:231], off
	v_lshl_add_u64 v[230:231], v[208:209], 0, s[42:43]
	s_mov_b32 m0, s73
	v_lshl_add_u64 v[208:209], v[208:209], 0, s[44:45]
	global_load_lds_dwordx4 v[230:231], off
	s_add_i32 m0, s73, 0x2000
	s_nop 0
	global_load_lds_dwordx4 v[208:209], off
	v_lshl_add_u64 v[208:209], v[228:229], 0, s[38:39]
	s_mov_b32 m0, s74
	s_nop 0
	global_load_lds_dwordx4 v[208:209], off
	v_lshl_add_u64 v[208:209], v[228:229], 0, s[40:41]
	s_mov_b32 m0, s75
	s_nop 0
	global_load_lds_dwordx4 v[208:209], off
	s_waitcnt vmcnt(8)
	s_waitcnt lgkmcnt(0)
	s_barrier
	s_waitcnt lgkmcnt(0)
	v_mfma_f32_16x16x32_bf16 v[60:63], v[128:131], v[160:163], v[60:63]
	v_mfma_f32_16x16x32_bf16 v[56:59], v[136:139], v[160:163], v[56:59]
	v_mfma_f32_16x16x32_bf16 v[44:47], v[128:131], v[168:171], v[44:47]
	v_mfma_f32_16x16x32_bf16 v[40:43], v[136:139], v[168:171], v[40:43]
	v_mfma_f32_16x16x32_bf16 v[28:31], v[128:131], v[176:179], v[28:31]
	v_mfma_f32_16x16x32_bf16 v[24:27], v[136:139], v[176:179], v[24:27]
	v_mfma_f32_16x16x32_bf16 v[12:15], v[128:131], v[220:223], v[12:15]
	v_mfma_f32_16x16x32_bf16 v[8:11], v[136:139], v[220:223], v[8:11]
	v_mfma_f32_16x16x32_bf16 v[60:63], v[132:135], v[164:167], v[60:63]
	v_mfma_f32_16x16x32_bf16 v[56:59], v[140:143], v[164:167], v[56:59]
	v_mfma_f32_16x16x32_bf16 v[44:47], v[132:135], v[172:175], v[44:47]
	v_mfma_f32_16x16x32_bf16 v[40:43], v[140:143], v[172:175], v[40:43]
	v_mfma_f32_16x16x32_bf16 v[28:31], v[132:135], v[180:183], v[28:31]
	v_mfma_f32_16x16x32_bf16 v[24:27], v[140:143], v[180:183], v[24:27]
	v_mfma_f32_16x16x32_bf16 v[12:15], v[132:135], v[224:227], v[12:15]
	v_mfma_f32_16x16x32_bf16 v[8:11], v[140:143], v[224:227], v[8:11]
	v_mfma_f32_16x16x32_bf16 v[52:55], v[144:147], v[160:163], v[52:55]
	v_mfma_f32_16x16x32_bf16 v[48:51], v[152:155], v[160:163], v[48:51]
	v_mfma_f32_16x16x32_bf16 v[36:39], v[144:147], v[168:171], v[36:39]
	v_mfma_f32_16x16x32_bf16 v[32:35], v[152:155], v[168:171], v[32:35]
	v_mfma_f32_16x16x32_bf16 v[20:23], v[144:147], v[176:179], v[20:23]
	v_mfma_f32_16x16x32_bf16 v[16:19], v[152:155], v[176:179], v[16:19]
	v_mfma_f32_16x16x32_bf16 v[4:7], v[144:147], v[220:223], v[4:7]
	v_mfma_f32_16x16x32_bf16 v[0:3], v[152:155], v[220:223], v[0:3]
	v_mfma_f32_16x16x32_bf16 v[52:55], v[148:151], v[164:167], v[52:55]
	v_mfma_f32_16x16x32_bf16 v[48:51], v[156:159], v[164:167], v[48:51]
	v_mfma_f32_16x16x32_bf16 v[36:39], v[148:151], v[172:175], v[36:39]
	v_mfma_f32_16x16x32_bf16 v[32:35], v[156:159], v[172:175], v[32:35]
	v_mfma_f32_16x16x32_bf16 v[20:23], v[148:151], v[180:183], v[20:23]
	v_mfma_f32_16x16x32_bf16 v[16:19], v[156:159], v[180:183], v[16:19]
	v_mfma_f32_16x16x32_bf16 v[4:7], v[148:151], v[224:227], v[4:7]
	v_mfma_f32_16x16x32_bf16 v[0:3], v[156:159], v[224:227], v[0:3]
	s_barrier
	s_add_i32 s72, s72, 2
	s_add_u32 s68, s68, 0x10000
	s_addc_u32 s69, s69, 0
	s_add_u32 s70, s70, 0x10000
	s_addc_u32 s71, s71, 0
	s_cmp_gt_u32 s72, 13
	s_add_i32 s76, s76, 1
	s_mul_i32 s4, s76, s80
	s_mul_hi_u32 s5, s76, s81
	s_add_i32 s5, s5, s4
	s_mul_i32 s4, s76, s81
	s_add_u32 s60, s4, s16
	s_addc_u32 s61, s5, s82
	v_cmp_gt_i64_e32 vcc, s[60:61], v[206:207]
	v_cmp_lt_i64_e64 s[4:5], s[60:61], v[204:205]
	s_cbranch_vccnz .LBB0_750
	s_ashr_i32 s56, s60, 31
	s_lshr_b32 s56, s56, 29
	s_add_i32 s58, s60, s56
	s_and_b32 s56, s58, -8
	s_sub_i32 s59, s60, s56
	s_cmp_gt_i32 s59, -1
	s_mov_b64 s[56:57], -1
	s_cbranch_scc0 .LBB0_747
	s_lshl_b32 s60, s59, 6
	s_mov_b64 s[56:57], 0

; template <class Epi, class Sched, bool ALIGN_EPI = false, bool SP2 = false>
; __device__ __forceinline__ void gemm_phase(PG8_LAS unsigned char* lds, const Gemm g, const Sched& S, const Epi& E) {
;     ...
;         const bool has_next = S.next(ui + 1, nxt);
;         const char* nA = has_next ? (const char*)g.A + (size_t)nxt.pm * tstepA : cA; const char* nB = has_next ? (const char*)g.Bt + (size_t)nxt.pn * tstepB : cB;
.LBB0_750:
	s_ashr_i32 s59, s58, 31
	s_lshl_b64 s[60:61], s[58:59], 19
	s_add_u32 s60, s6, s60
	s_addc_u32 s61, s7, s61
	s_and_b64 s[62:63], s[4:5], exec
	s_cselect_b32 s59, s61, s69
	s_cselect_b32 s65, s60, s68
	s_ashr_i32 s57, s56, 31
	s_lshl_b64 s[62:63], s[56:57], 19
	s_add_u32 s62, s93, s62
	s_addc_u32 s63, s84, s63
	s_and_b64 s[98:99], s[4:5], exec
	s_cselect_b32 s57, s63, s71
	s_cselect_b32 s67, s62, s70

; #define PG8_STAGE(bufoff, gbase, voff) do { _Pragma("unroll") for (int _i = 0; _i < 2; ++_i) \
;         __builtin_amdgcn_global_load_lds((const unsigned*)((const char*)(gbase) + (voff)[_i]), (PG8_LAS unsigned*)(lds + (bufoff) + ldsw + _i * 8192), 16, 0, 0); } while (0)
; #define PG8_LDA(dst, b, h) do { _Pragma("unroll") for (int m = 0; m < 4; ++m) _Pragma("unroll") for (int k = 0; k < 2; ++k) dst[m][k] = *(const PG8_LAS bf16x8*)(lds + PG8_SA(b, h) + aoff + m * 2048 + k * 1024); } while (0)
; #define PG8_LDB(dst, b, h) do { _Pragma("unroll") for (int n = 0; n < 2; ++n) _Pragma("unroll") for (int k = 0; k < 2; ++k) dst[n][k] = *(const PG8_LAS bf16x8*)(lds + PG8_SB(b, h) + boff + n * 2048 + k * 1024); } while (0)
; #define PG8_MMA(ai, bj, At, Bt) do { __builtin_amdgcn_s_setprio(1); _Pragma("unroll") for (int m = 0; m < 4; ++m) _Pragma("unroll") for (int n = 0; n < 2; ++n) _Pragma("unroll") for (int k = 0; k < 2; ++k) \
;         acc[ai][bj][m][n] = __builtin_amdgcn_mfma_f32_16x16x32_bf16(Bt[n][k], At[m][k], acc[ai][bj][m][n], 0, 0, 0); __builtin_amdgcn_s_setprio(0); } while (0)
; #define PG8_WAIT_V(n) asm volatile("s_waitcnt vmcnt(" #n ")" ::: "memory")
; #define PG8_WAIT_L(n) asm volatile("s_waitcnt lgkmcnt(" #n ")" ::: "memory")
; #define PG8_BAR __builtin_amdgcn_s_barrier()
; #define PG8_SCHED __builtin_amdgcn_sched_barrier(0)
; template <class Epi, class Sched, bool ALIGN_EPI = false, bool SP2 = false>
; __device__ __forceinline__ void gemm_phase(PG8_LAS unsigned char* lds, const Gemm g, const Sched& S, const Epi& E) {
;     ...
;         const bool has_next = S.next(ui + 1, nxt);
;         const char* nA = has_next ? (const char*)g.A + (size_t)nxt.pm * tstepA : cA; const char* nB = has_next ? (const char*)g.Bt + (size_t)nxt.pn * tstepB : cB;
;     ...
;             PG8_LDB(B0, 0, 0); PG8_LDB(B1, 0, 1); PG8_SCHED; PG8_LDA(At, 0, 0); PG8_STAGE(PG8_SA(1, 1), a1 + hstepA, voffA);
;             PG8_WAIT_V(8); PG8_WAIT_L(0); PG8_BAR; PG8_MMA(0, 0, At, B0); PG8_MMA(0, 1, At, B1); PG8_BAR; PG8_SCHED;
;             PG8_LDA(At, 0, 1); PG8_STAGE(PG8_SB(0, 0), b2, voffB); PG8_STAGE(PG8_SB(0, 1), b2 + hstepB, voffB); PG8_STAGE(PG8_SA(0, 0), a2, voffA);
;             PG8_WAIT_V(8); PG8_WAIT_L(0); PG8_BAR; PG8_MMA(1, 0, At, B0); PG8_MMA(1, 1, At, B1); PG8_BAR; PG8_SCHED;
.LBB0_835:
	s_add_u32 s62, s62, 0x10000
	s_addc_u32 s63, s63, 0
	s_add_u32 s64, s64, 0x10000
	s_addc_u32 s65, s65, 0
	s_mov_b32 s82, -2
	ds_read_b128 v[148:151], v141
	ds_read_b128 v[152:155], v141 offset:1024
	ds_read_b128 v[156:159], v141 offset:2048
	ds_read_b128 v[160:163], v141 offset:3072
	ds_read_b128 v[164:167], v142
	ds_read_b128 v[168:171], v142 offset:1024
	ds_read_b128 v[172:175], v142 offset:2048
	ds_read_b128 v[176:179], v142 offset:3072
	s_cmp_eq_u32 s82, 12
	s_cselect_b32 s79, s55, s63
	s_cselect_b32 s78, s80, s62
	s_cselect_b32 s85, s53, s65
	s_cselect_b32 s84, s81, s64
	v_lshl_add_u64 v[216:217], s[62:63], 0, v[190:191]
	v_lshl_add_u64 v[220:221], v[216:217], 0, s[46:47]
	s_add_i32 m0, s18, 0xc000
	ds_read_b128 v[180:183], v143
	ds_read_b128 v[184:187], v143 offset:1024
	ds_read_b128 v[192:195], v143 offset:2048
	ds_read_b128 v[196:199], v143 offset:3072
	ds_read_b128 v[200:203], v143 offset:4096
	ds_read_b128 v[204:207], v143 offset:5120
	ds_read_b128 v[208:211], v143 offset:6144
	ds_read_b128 v[212:215], v143 offset:7168
	global_load_lds_dwordx4 v[220:221], off
	v_lshl_add_u64 v[216:217], v[216:217], 0, s[48:49]
	s_add_i32 m0, s18, 0xe000
	s_nop 0
	global_load_lds_dwordx4 v[216:217], off
	s_waitcnt vmcnt(8)
	s_waitcnt lgkmcnt(0)
	s_barrier
	s_waitcnt lgkmcnt(0)
	v_mfma_f32_16x16x32_bf16 v[116:119], v[148:151], v[180:183], 0
	v_mfma_f32_16x16x32_bf16 v[112:115], v[156:159], v[180:183], 0
	v_mfma_f32_16x16x32_bf16 v[108:111], v[148:151], v[192:195], 0
	v_mfma_f32_16x16x32_bf16 v[100:103], v[156:159], v[192:195], 0
	v_mfma_f32_16x16x32_bf16 v[92:95], v[148:151], v[200:203], 0
	v_mfma_f32_16x16x32_bf16 v[84:87], v[156:159], v[200:203], 0
	v_mfma_f32_16x16x32_bf16 v[76:79], v[148:151], v[208:211], 0
	v_mfma_f32_16x16x32_bf16 v[68:71], v[156:159], v[208:211], 0
	v_mfma_f32_16x16x32_bf16 v[116:119], v[152:155], v[184:187], v[116:119]
	v_mfma_f32_16x16x32_bf16 v[112:115], v[160:163], v[184:187], v[112:115]
	v_mfma_f32_16x16x32_bf16 v[108:111], v[152:155], v[196:199], v[108:111]
	v_mfma_f32_16x16x32_bf16 v[100:103], v[160:163], v[196:199], v[100:103]
	v_mfma_f32_16x16x32_bf16 v[92:95], v[152:155], v[204:207], v[92:95]
	v_mfma_f32_16x16x32_bf16 v[84:87], v[160:163], v[204:207], v[84:87]
	v_mfma_f32_16x16x32_bf16 v[76:79], v[152:155], v[212:215], v[76:79]
	v_mfma_f32_16x16x32_bf16 v[68:71], v[160:163], v[212:215], v[68:71]
	v_mfma_f32_16x16x32_bf16 v[124:127], v[164:167], v[180:183], 0
	v_mfma_f32_16x16x32_bf16 v[120:123], v[172:175], v[180:183], 0
	v_mfma_f32_16x16x32_bf16 v[104:107], v[164:167], v[192:195], 0
	v_mfma_f32_16x16x32_bf16 v[96:99], v[172:175], v[192:195], 0
	v_mfma_f32_16x16x32_bf16 v[88:91], v[164:167], v[200:203], 0
	v_mfma_f32_16x16x32_bf16 v[80:83], v[172:175], v[200:203], 0
	v_mfma_f32_16x16x32_bf16 v[72:75], v[164:167], v[208:211], 0
	v_mfma_f32_16x16x32_bf16 v[64:67], v[172:175], v[208:211], 0
	v_mfma_f32_16x16x32_bf16 v[124:127], v[168:171], v[184:187], v[124:127]
	v_mfma_f32_16x16x32_bf16 v[120:123], v[176:179], v[184:187], v[120:123]
	v_mfma_f32_16x16x32_bf16 v[104:107], v[168:171], v[196:199], v[104:107]
	v_mfma_f32_16x16x32_bf16 v[96:99], v[176:179], v[196:199], v[96:99]
	v_mfma_f32_16x16x32_bf16 v[88:91], v[168:171], v[204:207], v[88:91]
	v_mfma_f32_16x16x32_bf16 v[80:83], v[176:179], v[204:207], v[80:83]
	v_mfma_f32_16x16x32_bf16 v[72:75], v[168:171], v[212:215], v[72:75]
	v_mfma_f32_16x16x32_bf16 v[64:67], v[176:179], v[212:215], v[64:67]
	s_barrier
	v_lshl_add_u64 v[216:217], s[84:85], 0, v[190:191]
	s_add_i32 s84, s74, s14
	s_mov_b32 m0, s84
	ds_read_b128 v[180:183], v143 offset:16384
	ds_read_b128 v[184:187], v143 offset:17408
	ds_read_b128 v[192:195], v143 offset:18432
	ds_read_b128 v[196:199], v143 offset:19456
	ds_read_b128 v[200:203], v143 offset:20480
	ds_read_b128 v[204:207], v143 offset:21504
	ds_read_b128 v[208:211], v143 offset:22528
	ds_read_b128 v[212:215], v143 offset:23552
	global_load_lds_dwordx4 v[216:217], off
	v_lshl_add_u64 v[220:221], v[216:217], 0, s[6:7]
	s_add_i32 m0, s84, 0x2000
	s_add_i32 s84, s75, s14
	global_load_lds_dwordx4 v[220:221], off
	v_lshl_add_u64 v[220:221], v[216:217], 0, s[8:9]
	s_mov_b32 m0, s84
	s_nop 0
	global_load_lds_dwordx4 v[220:221], off
	v_lshl_add_u64 v[220:221], v[216:217], 0, s[10:11]
	s_add_i32 m0, s84, 0x2000
	s_nop 0
	global_load_lds_dwordx4 v[220:221], off
	v_lshl_add_u64 v[220:221], s[78:79], 0, v[190:191]
	s_mov_b32 m0, s18
	v_lshl_add_u64 v[222:223], v[220:221], 0, s[6:7]
	global_load_lds_dwordx4 v[220:221], off
	s_mov_b32 m0, s19
	s_nop 0
	global_load_lds_dwordx4 v[222:223], off
	s_waitcnt vmcnt(8)
	s_waitcnt lgkmcnt(0)
	s_barrier
; #define PG8_STAGE(bufoff, gbase, voff) do { _Pragma("unroll") for (int _i = 0; _i < 2; ++_i) \
;         __builtin_amdgcn_global_load_lds((const unsigned*)((const char*)(gbase) + (voff)[_i]), (PG8_LAS unsigned*)(lds + (bufoff) + ldsw + _i * 8192), 16, 0, 0); } while (0)
; #define PG8_LDA(dst, b, h) do { _Pragma("unroll") for (int m = 0; m < 4; ++m) _Pragma("unroll") for (int k = 0; k < 2; ++k) dst[m][k] = *(const PG8_LAS bf16x8*)(lds + PG8_SA(b, h) + aoff + m * 2048 + k * 1024); } while (0)
; #define PG8_LDB(dst, b, h) do { _Pragma("unroll") for (int n = 0; n < 2; ++n) _Pragma("unroll") for (int k = 0; k < 2; ++k) dst[n][k] = *(const PG8_LAS bf16x8*)(lds + PG8_SB(b, h) + boff + n * 2048 + k * 1024); } while (0)
; #define PG8_MMA(ai, bj, At, Bt) do { __builtin_amdgcn_s_setprio(1); _Pragma("unroll") for (int m = 0; m < 4; ++m) _Pragma("unroll") for (int n = 0; n < 2; ++n) _Pragma("unroll") for (int k = 0; k < 2; ++k) \
;         acc[ai][bj][m][n] = __builtin_amdgcn_mfma_f32_16x16x32_bf16(Bt[n][k], At[m][k], acc[ai][bj][m][n], 0, 0, 0); __builtin_amdgcn_s_setprio(0); } while (0)
; #define PG8_WAIT_V(n) asm volatile("s_waitcnt vmcnt(" #n ")" ::: "memory")
; #define PG8_WAIT_L(n) asm volatile("s_waitcnt lgkmcnt(" #n ")" ::: "memory")
; #define PG8_BAR __builtin_amdgcn_s_barrier()
; #define PG8_SCHED __builtin_amdgcn_sched_barrier(0)
; template <class Epi, class Sched, bool ALIGN_EPI = false, bool SP2 = false>
; __device__ __forceinline__ void gemm_phase(PG8_LAS unsigned char* lds, const Gemm g, const Sched& S, const Epi& E) {
;     ...
;             PG8_WAIT_V(8); PG8_WAIT_L(0); PG8_BAR; PG8_MMA(1, 0, At, B0); PG8_MMA(1, 1, At, B1); PG8_BAR; PG8_SCHED;
;             PG8_LDB(B0, 1, 0); PG8_LDB(B1, 1, 1); PG8_SCHED; PG8_LDA(At, 1, 0); PG8_STAGE(PG8_SA(0, 1), a2 + hstepA, voffA);
;             PG8_WAIT_V(8); PG8_WAIT_L(0); PG8_BAR; PG8_MMA(0, 0, At, B0); PG8_MMA(0, 1, At, B1); PG8_BAR; PG8_SCHED;
	s_waitcnt lgkmcnt(0)
	v_mfma_f32_16x16x32_bf16 v[60:63], v[148:151], v[180:183], 0
	v_mfma_f32_16x16x32_bf16 v[52:55], v[156:159], v[180:183], 0
	v_mfma_f32_16x16x32_bf16 v[44:47], v[148:151], v[192:195], 0
	v_mfma_f32_16x16x32_bf16 v[36:39], v[156:159], v[192:195], 0
	v_mfma_f32_16x16x32_bf16 v[28:31], v[148:151], v[200:203], 0
	v_mfma_f32_16x16x32_bf16 v[20:23], v[156:159], v[200:203], 0
	v_mfma_f32_16x16x32_bf16 v[12:15], v[148:151], v[208:211], 0
	v_mfma_f32_16x16x32_bf16 v[4:7], v[156:159], v[208:211], 0
	v_mfma_f32_16x16x32_bf16 v[60:63], v[152:155], v[184:187], v[60:63]
	v_mfma_f32_16x16x32_bf16 v[52:55], v[160:163], v[184:187], v[52:55]
	v_mfma_f32_16x16x32_bf16 v[44:47], v[152:155], v[196:199], v[44:47]
	v_mfma_f32_16x16x32_bf16 v[36:39], v[160:163], v[196:199], v[36:39]
	v_mfma_f32_16x16x32_bf16 v[28:31], v[152:155], v[204:207], v[28:31]
	v_mfma_f32_16x16x32_bf16 v[20:23], v[160:163], v[204:207], v[20:23]
	v_mfma_f32_16x16x32_bf16 v[12:15], v[152:155], v[212:215], v[12:15]
	v_mfma_f32_16x16x32_bf16 v[4:7], v[160:163], v[212:215], v[4:7]
	v_mfma_f32_16x16x32_bf16 v[56:59], v[164:167], v[180:183], 0
	v_mfma_f32_16x16x32_bf16 v[48:51], v[172:175], v[180:183], 0
	v_mfma_f32_16x16x32_bf16 v[40:43], v[164:167], v[192:195], 0
	v_mfma_f32_16x16x32_bf16 v[32:35], v[172:175], v[192:195], 0
	v_mfma_f32_16x16x32_bf16 v[24:27], v[164:167], v[200:203], 0
	v_mfma_f32_16x16x32_bf16 v[16:19], v[172:175], v[200:203], 0
	v_mfma_f32_16x16x32_bf16 v[8:11], v[164:167], v[208:211], 0
	v_mfma_f32_16x16x32_bf16 v[0:3], v[172:175], v[208:211], 0
	v_mfma_f32_16x16x32_bf16 v[56:59], v[168:171], v[184:187], v[56:59]
	v_mfma_f32_16x16x32_bf16 v[48:51], v[176:179], v[184:187], v[48:51]
	v_mfma_f32_16x16x32_bf16 v[40:43], v[168:171], v[196:199], v[40:43]
	v_mfma_f32_16x16x32_bf16 v[32:35], v[176:179], v[196:199], v[32:35]
	v_mfma_f32_16x16x32_bf16 v[24:27], v[168:171], v[204:207], v[24:27]
	v_mfma_f32_16x16x32_bf16 v[16:19], v[176:179], v[204:207], v[16:19]
	v_mfma_f32_16x16x32_bf16 v[8:11], v[168:171], v[212:215], v[8:11]
	v_mfma_f32_16x16x32_bf16 v[0:3], v[176:179], v[212:215], v[0:3]
	s_barrier
	ds_read_b128 v[148:151], v144
	ds_read_b128 v[152:155], v144 offset:1024
	ds_read_b128 v[156:159], v144 offset:2048
	ds_read_b128 v[160:163], v144 offset:3072
	ds_read_b128 v[164:167], v145
	ds_read_b128 v[168:171], v145 offset:1024
	ds_read_b128 v[172:175], v145 offset:2048
	ds_read_b128 v[176:179], v145 offset:3072
	s_mov_b32 m0, s66
	v_lshl_add_u64 v[222:223], v[220:221], 0, s[8:9]
	ds_read_b128 v[180:183], v143 offset:32768
	ds_read_b128 v[184:187], v143 offset:33792
	ds_read_b128 v[192:195], v143 offset:34816
	ds_read_b128 v[196:199], v143 offset:35840
	ds_read_b128 v[200:203], v143 offset:36864
	ds_read_b128 v[204:207], v143 offset:37888
	ds_read_b128 v[208:211], v143 offset:38912
	ds_read_b128 v[212:215], v143 offset:39936
	global_load_lds_dwordx4 v[222:223], off
	v_lshl_add_u64 v[222:223], v[220:221], 0, s[10:11]
	s_mov_b32 m0, s67
	s_nop 0
	global_load_lds_dwordx4 v[222:223], off
	s_waitcnt vmcnt(8)
	s_waitcnt lgkmcnt(0)
	s_barrier
	s_waitcnt lgkmcnt(0)
	v_mfma_f32_16x16x32_bf16 v[116:119], v[148:151], v[180:183], v[116:119]
	v_mfma_f32_16x16x32_bf16 v[112:115], v[156:159], v[180:183], v[112:115]
	v_mfma_f32_16x16x32_bf16 v[108:111], v[148:151], v[192:195], v[108:111]
	v_mfma_f32_16x16x32_bf16 v[100:103], v[156:159], v[192:195], v[100:103]
	v_mfma_f32_16x16x32_bf16 v[92:95], v[148:151], v[200:203], v[92:95]
	v_mfma_f32_16x16x32_bf16 v[84:87], v[156:159], v[200:203], v[84:87]
	v_mfma_f32_16x16x32_bf16 v[76:79], v[148:151], v[208:211], v[76:79]
	v_mfma_f32_16x16x32_bf16 v[68:71], v[156:159], v[208:211], v[68:71]
	v_mfma_f32_16x16x32_bf16 v[116:119], v[152:155], v[184:187], v[116:119]
	v_mfma_f32_16x16x32_bf16 v[112:115], v[160:163], v[184:187], v[112:115]
	v_mfma_f32_16x16x32_bf16 v[108:111], v[152:155], v[196:199], v[108:111]
	v_mfma_f32_16x16x32_bf16 v[100:103], v[160:163], v[196:199], v[100:103]
	v_mfma_f32_16x16x32_bf16 v[92:95], v[152:155], v[204:207], v[92:95]
	v_mfma_f32_16x16x32_bf16 v[84:87], v[160:163], v[204:207], v[84:87]
	v_mfma_f32_16x16x32_bf16 v[76:79], v[152:155], v[212:215], v[76:79]
	v_mfma_f32_16x16x32_bf16 v[68:71], v[160:163], v[212:215], v[68:71]
	v_mfma_f32_16x16x32_bf16 v[124:127], v[164:167], v[180:183], v[124:127]
	v_mfma_f32_16x16x32_bf16 v[120:123], v[172:175], v[180:183], v[120:123]
	v_mfma_f32_16x16x32_bf16 v[104:107], v[164:167], v[192:195], v[104:107]
	v_mfma_f32_16x16x32_bf16 v[96:99], v[172:175], v[192:195], v[96:99]
	v_mfma_f32_16x16x32_bf16 v[88:91], v[164:167], v[200:203], v[88:91]
	v_mfma_f32_16x16x32_bf16 v[80:83], v[172:175], v[200:203], v[80:83]
	v_mfma_f32_16x16x32_bf16 v[72:75], v[164:167], v[208:211], v[72:75]
	v_mfma_f32_16x16x32_bf16 v[64:67], v[172:175], v[208:211], v[64:67]
	v_mfma_f32_16x16x32_bf16 v[124:127], v[168:171], v[184:187], v[124:127]
	v_mfma_f32_16x16x32_bf16 v[120:123], v[176:179], v[184:187], v[120:123]
	v_mfma_f32_16x16x32_bf16 v[104:107], v[168:171], v[196:199], v[104:107]
	v_mfma_f32_16x16x32_bf16 v[96:99], v[176:179], v[196:199], v[96:99]
	v_mfma_f32_16x16x32_bf16 v[88:91], v[168:171], v[204:207], v[88:91]
	v_mfma_f32_16x16x32_bf16 v[80:83], v[176:179], v[204:207], v[80:83]
	v_mfma_f32_16x16x32_bf16 v[72:75], v[168:171], v[212:215], v[72:75]
	v_mfma_f32_16x16x32_bf16 v[64:67], v[176:179], v[212:215], v[64:67]
	s_barrier
; #define PG8_STAGE(bufoff, gbase, voff) do { _Pragma("unroll") for (int _i = 0; _i < 2; ++_i) \
;         __builtin_amdgcn_global_load_lds((const unsigned*)((const char*)(gbase) + (voff)[_i]), (PG8_LAS unsigned*)(lds + (bufoff) + ldsw + _i * 8192), 16, 0, 0); } while (0)
; #define PG8_LDA(dst, b, h) do { _Pragma("unroll") for (int m = 0; m < 4; ++m) _Pragma("unroll") for (int k = 0; k < 2; ++k) dst[m][k] = *(const PG8_LAS bf16x8*)(lds + PG8_SA(b, h) + aoff + m * 2048 + k * 1024); } while (0)
; #define PG8_MMA(ai, bj, At, Bt) do { __builtin_amdgcn_s_setprio(1); _Pragma("unroll") for (int m = 0; m < 4; ++m) _Pragma("unroll") for (int n = 0; n < 2; ++n) _Pragma("unroll") for (int k = 0; k < 2; ++k) \
;         acc[ai][bj][m][n] = __builtin_amdgcn_mfma_f32_16x16x32_bf16(Bt[n][k], At[m][k], acc[ai][bj][m][n], 0, 0, 0); __builtin_amdgcn_s_setprio(0); } while (0)
; #define PG8_WAIT_V(n) asm volatile("s_waitcnt vmcnt(" #n ")" ::: "memory")
; #define PG8_WAIT_L(n) asm volatile("s_waitcnt lgkmcnt(" #n ")" ::: "memory")
; #define PG8_BAR __builtin_amdgcn_s_barrier()
; #define PG8_SCHED __builtin_amdgcn_sched_barrier(0)
;     __host__ __device__ bool next(int i, Unit& u) const {
;         const long L = (long)i * G + c; if (L >= nwg) return false;
;         int wgid = (int)L; { const int q = nwg / NXCD, r = nwg % NXCD, xcd = wgid % NXCD, off = wgid / NXCD; wgid = (xcd < r ? xcd * (q + 1) : r * (q + 1) + (xcd - r) * q) + off; }
;         const int nig = wgm * nN, gid = wgid / nig, fm = gid * wgm, gsz = (nM - fm) < wgm ? (nM - fm) : wgm;
;         u.pm = fm + ((wgid % nig) % gsz); u.pn = (wgid % nig) / gsz; return true;
; template <class Epi, class Sched, bool ALIGN_EPI = false, bool SP2 = false>
; __device__ __forceinline__ void gemm_phase(PG8_LAS unsigned char* lds, const Gemm g, const Sched& S, const Epi& E) {
;     ...
;             PG8_LDA(At, 1, 1); PG8_STAGE(PG8_SB(1, 0), b3, voffB); PG8_STAGE(PG8_SB(1, 1), b3 + hstepB, voffB); PG8_STAGE(PG8_SA(1, 0), a3, voffA);
;             PG8_WAIT_V(8); PG8_WAIT_L(0); PG8_BAR; PG8_MMA(1, 0, At, B0); PG8_MMA(1, 1, At, B1); PG8_BAR; PG8_SCHED;
	s_add_i32 s78, s76, s14
	v_lshl_add_u64 v[222:223], v[216:217], 0, s[34:35]
	s_mov_b32 m0, s78
	ds_read_b128 v[180:183], v143 offset:49152
	ds_read_b128 v[184:187], v143 offset:50176
	ds_read_b128 v[192:195], v143 offset:51200
	ds_read_b128 v[196:199], v143 offset:52224
	ds_read_b128 v[200:203], v143 offset:53248
	ds_read_b128 v[204:207], v143 offset:54272
	ds_read_b128 v[208:211], v143 offset:55296
	ds_read_b128 v[212:215], v143 offset:56320
	global_load_lds_dwordx4 v[222:223], off
	v_lshl_add_u64 v[222:223], v[216:217], 0, s[36:37]
	s_add_i32 m0, s78, 0x2000
	s_add_i32 s78, s77, s14
	global_load_lds_dwordx4 v[222:223], off
	v_lshl_add_u64 v[222:223], v[216:217], 0, s[38:39]
	s_mov_b32 m0, s78
	v_lshl_add_u64 v[216:217], v[216:217], 0, s[40:41]
	global_load_lds_dwordx4 v[222:223], off
	s_add_i32 m0, s78, 0x2000
	s_nop 0
	global_load_lds_dwordx4 v[216:217], off
	v_lshl_add_u64 v[216:217], v[220:221], 0, s[34:35]
	s_mov_b32 m0, s68
	s_nop 0
	global_load_lds_dwordx4 v[216:217], off
	v_lshl_add_u64 v[216:217], v[220:221], 0, s[36:37]
	s_mov_b32 m0, s69
	s_nop 0
	global_load_lds_dwordx4 v[216:217], off
	s_waitcnt vmcnt(8)
	s_waitcnt lgkmcnt(0)
	s_barrier
	s_waitcnt lgkmcnt(0)
	v_mfma_f32_16x16x32_bf16 v[60:63], v[148:151], v[180:183], v[60:63]
	v_mfma_f32_16x16x32_bf16 v[52:55], v[156:159], v[180:183], v[52:55]
	v_mfma_f32_16x16x32_bf16 v[44:47], v[148:151], v[192:195], v[44:47]
	v_mfma_f32_16x16x32_bf16 v[36:39], v[156:159], v[192:195], v[36:39]
	v_mfma_f32_16x16x32_bf16 v[28:31], v[148:151], v[200:203], v[28:31]
	v_mfma_f32_16x16x32_bf16 v[20:23], v[156:159], v[200:203], v[20:23]
	v_mfma_f32_16x16x32_bf16 v[12:15], v[148:151], v[208:211], v[12:15]
	v_mfma_f32_16x16x32_bf16 v[4:7], v[156:159], v[208:211], v[4:7]
	v_mfma_f32_16x16x32_bf16 v[60:63], v[152:155], v[184:187], v[60:63]
	v_mfma_f32_16x16x32_bf16 v[52:55], v[160:163], v[184:187], v[52:55]
	v_mfma_f32_16x16x32_bf16 v[44:47], v[152:155], v[196:199], v[44:47]
	v_mfma_f32_16x16x32_bf16 v[36:39], v[160:163], v[196:199], v[36:39]
	v_mfma_f32_16x16x32_bf16 v[28:31], v[152:155], v[204:207], v[28:31]
	v_mfma_f32_16x16x32_bf16 v[20:23], v[160:163], v[204:207], v[20:23]
	v_mfma_f32_16x16x32_bf16 v[12:15], v[152:155], v[212:215], v[12:15]
	v_mfma_f32_16x16x32_bf16 v[4:7], v[160:163], v[212:215], v[4:7]
	v_mfma_f32_16x16x32_bf16 v[56:59], v[164:167], v[180:183], v[56:59]
	v_mfma_f32_16x16x32_bf16 v[48:51], v[172:175], v[180:183], v[48:51]
	v_mfma_f32_16x16x32_bf16 v[40:43], v[164:167], v[192:195], v[40:43]
	v_mfma_f32_16x16x32_bf16 v[32:35], v[172:175], v[192:195], v[32:35]
	v_mfma_f32_16x16x32_bf16 v[24:27], v[164:167], v[200:203], v[24:27]
	v_mfma_f32_16x16x32_bf16 v[16:19], v[172:175], v[200:203], v[16:19]
	v_mfma_f32_16x16x32_bf16 v[8:11], v[164:167], v[208:211], v[8:11]
	v_mfma_f32_16x16x32_bf16 v[0:3], v[172:175], v[208:211], v[0:3]
	v_mfma_f32_16x16x32_bf16 v[56:59], v[168:171], v[184:187], v[56:59]
	v_mfma_f32_16x16x32_bf16 v[48:51], v[176:179], v[184:187], v[48:51]
	v_mfma_f32_16x16x32_bf16 v[40:43], v[168:171], v[196:199], v[40:43]
	v_mfma_f32_16x16x32_bf16 v[32:35], v[176:179], v[196:199], v[32:35]
	v_mfma_f32_16x16x32_bf16 v[24:27], v[168:171], v[204:207], v[24:27]
	v_mfma_f32_16x16x32_bf16 v[16:19], v[176:179], v[204:207], v[16:19]
	v_mfma_f32_16x16x32_bf16 v[8:11], v[168:171], v[212:215], v[8:11]
	v_mfma_f32_16x16x32_bf16 v[0:3], v[176:179], v[212:215], v[0:3]
	s_barrier
	s_add_i32 s82, s82, 2
	s_add_u32 s62, s62, 0x10000
	s_addc_u32 s63, s63, 0
	s_add_u32 s64, s64, 0x10000
	s_addc_u32 s65, s65, 0
	s_cmp_gt_u32 s82, 13
	s_add_i32 s70, s70, 1
	s_mul_i32 s2, s70, s72
	s_mul_hi_u32 s3, s70, s73
	s_add_i32 s3, s3, s2
	s_mul_i32 s2, s70, s73
	s_add_u32 s56, s2, s16
	s_addc_u32 s57, s3, s15
	v_cmp_gt_i64_e32 vcc, s[56:57], v[138:139]
	v_cmp_lt_i64_e64 s[2:3], s[56:57], v[136:137]
	s_cbranch_vccnz .LBB0_837
	s_ashr_i32 s52, s56, 31
	s_lshr_b32 s52, s52, 29
	s_add_i32 s52, s56, s52
	s_ashr_i32 s53, s52, 3
	s_and_b32 s52, s52, -8
	s_sub_i32 s52, s56, s52
	s_cmp_lt_i32 s52, 0
	s_cselect_b32 s54, s17, 0x160
	s_mul_i32 s52, s52, s54
	s_add_i32 s52, s52, s53
	s_mul_hi_i32 s53, s52, 0x2e8ba2e9
	s_lshr_b32 s54, s53, 31
	s_ashr_i32 s53, s53, 4
	s_add_i32 s53, s53, s54
	s_lshl_b32 s54, s53, 2
	s_mulk_i32 s53, 0x58
	s_sub_i32 s53, s52, s53
	s_abs_i32 s52, s53
	s_ashr_i32 s52, s53, 2
	s_and_b32 s53, s53, 3
	s_add_i32 s54, s54, s53
.LBB0_837:
	s_ashr_i32 s55, s54, 31
	s_lshl_b64 s[56:57], s[54:55], 19
	s_add_u32 s56, s12, s56
	s_addc_u32 s57, s13, s57
	s_and_b64 s[58:59], s[2:3], exec
	s_cselect_b32 s55, s57, s63
	s_cselect_b32 s80, s56, s62
	s_ashr_i32 s53, s52, 31
	s_lshl_b64 s[58:59], s[52:53], 19
	s_add_u32 s58, s33, s58
	s_addc_u32 s59, s83, s59
	s_and_b64 s[78:79], s[2:3], exec
	s_cselect_b32 s53, s59, s65
	s_cselect_b32 s81, s58, s64
; #define PG8_STAGE(bufoff, gbase, voff) do { _Pragma("unroll") for (int _i = 0; _i < 2; ++_i) \
;         __builtin_amdgcn_global_load_lds((const unsigned*)((const char*)(gbase) + (voff)[_i]), (PG8_LAS unsigned*)(lds + (bufoff) + ldsw + _i * 8192), 16, 0, 0); } while (0)
; #define PG8_LDA(dst, b, h) do { _Pragma("unroll") for (int m = 0; m < 4; ++m) _Pragma("unroll") for (int k = 0; k < 2; ++k) dst[m][k] = *(const PG8_LAS bf16x8*)(lds + PG8_SA(b, h) + aoff + m * 2048 + k * 1024); } while (0)
; #define PG8_LDB(dst, b, h) do { _Pragma("unroll") for (int n = 0; n < 2; ++n) _Pragma("unroll") for (int k = 0; k < 2; ++k) dst[n][k] = *(const PG8_LAS bf16x8*)(lds + PG8_SB(b, h) + boff + n * 2048 + k * 1024); } while (0)
; #define PG8_MMA(ai, bj, At, Bt) do { __builtin_amdgcn_s_setprio(1); _Pragma("unroll") for (int m = 0; m < 4; ++m) _Pragma("unroll") for (int n = 0; n < 2; ++n) _Pragma("unroll") for (int k = 0; k < 2; ++k) \
;         acc[ai][bj][m][n] = __builtin_amdgcn_mfma_f32_16x16x32_bf16(Bt[n][k], At[m][k], acc[ai][bj][m][n], 0, 0, 0); __builtin_amdgcn_s_setprio(0); } while (0)
; #define PG8_WAIT_V(n) asm volatile("s_waitcnt vmcnt(" #n ")" ::: "memory")
; #define PG8_WAIT_L(n) asm volatile("s_waitcnt lgkmcnt(" #n ")" ::: "memory")
; #define PG8_BAR __builtin_amdgcn_s_barrier()
; #define PG8_SCHED __builtin_amdgcn_sched_barrier(0)
; template <class Epi, class Sched, bool ALIGN_EPI = false, bool SP2 = false>
; __device__ __forceinline__ void gemm_phase(PG8_LAS unsigned char* lds, const Gemm g, const Sched& S, const Epi& E) {
;     ...
;             PG8_LDB(B0, 0, 0); PG8_LDB(B1, 0, 1); PG8_SCHED; PG8_LDA(At, 0, 0); PG8_STAGE(PG8_SA(1, 1), a1 + hstepA, voffA);
;             PG8_WAIT_V(8); PG8_WAIT_L(0); PG8_BAR; PG8_MMA(0, 0, At, B0); PG8_MMA(0, 1, At, B1); PG8_BAR; PG8_SCHED;
;             PG8_LDA(At, 0, 1); PG8_STAGE(PG8_SB(0, 0), b2, voffB); PG8_STAGE(PG8_SB(0, 1), b2 + hstepB, voffB); PG8_STAGE(PG8_SA(0, 0), a2, voffA);
;             PG8_WAIT_V(8); PG8_WAIT_L(0); PG8_BAR; PG8_MMA(1, 0, At, B0); PG8_MMA(1, 1, At, B1); PG8_BAR; PG8_SCHED;
.LBB0_838:
	ds_read_b128 v[148:151], v141
	ds_read_b128 v[152:155], v141 offset:1024
	ds_read_b128 v[156:159], v141 offset:2048
	ds_read_b128 v[160:163], v141 offset:3072
	ds_read_b128 v[164:167], v142
	ds_read_b128 v[168:171], v142 offset:1024
	ds_read_b128 v[172:175], v142 offset:2048
	ds_read_b128 v[176:179], v142 offset:3072
	s_cmp_eq_u32 s82, 12
	s_cselect_b32 s79, s55, s63
	s_cselect_b32 s78, s80, s62
	s_cselect_b32 s85, s53, s65
	s_cselect_b32 s84, s81, s64
	v_lshl_add_u64 v[216:217], s[62:63], 0, v[190:191]
	v_lshl_add_u64 v[220:221], v[216:217], 0, s[46:47]
	s_add_i32 m0, s18, 0xc000
	ds_read_b128 v[180:183], v143
	ds_read_b128 v[184:187], v143 offset:1024
	ds_read_b128 v[192:195], v143 offset:2048
	ds_read_b128 v[196:199], v143 offset:3072
	ds_read_b128 v[200:203], v143 offset:4096
	ds_read_b128 v[204:207], v143 offset:5120
	ds_read_b128 v[208:211], v143 offset:6144
	ds_read_b128 v[212:215], v143 offset:7168
	global_load_lds_dwordx4 v[220:221], off
	v_lshl_add_u64 v[216:217], v[216:217], 0, s[48:49]
	s_add_i32 m0, s18, 0xe000
	s_nop 0
	global_load_lds_dwordx4 v[216:217], off
	s_waitcnt vmcnt(8)
	s_waitcnt lgkmcnt(0)
	s_barrier
	s_waitcnt lgkmcnt(0)
	v_mfma_f32_16x16x32_bf16 v[116:119], v[148:151], v[180:183], v[116:119]
	v_mfma_f32_16x16x32_bf16 v[112:115], v[156:159], v[180:183], v[112:115]
	v_mfma_f32_16x16x32_bf16 v[108:111], v[148:151], v[192:195], v[108:111]
	v_mfma_f32_16x16x32_bf16 v[100:103], v[156:159], v[192:195], v[100:103]
	v_mfma_f32_16x16x32_bf16 v[92:95], v[148:151], v[200:203], v[92:95]
	v_mfma_f32_16x16x32_bf16 v[84:87], v[156:159], v[200:203], v[84:87]
	v_mfma_f32_16x16x32_bf16 v[76:79], v[148:151], v[208:211], v[76:79]
	v_mfma_f32_16x16x32_bf16 v[68:71], v[156:159], v[208:211], v[68:71]
	v_mfma_f32_16x16x32_bf16 v[116:119], v[152:155], v[184:187], v[116:119]
	v_mfma_f32_16x16x32_bf16 v[112:115], v[160:163], v[184:187], v[112:115]
	v_mfma_f32_16x16x32_bf16 v[108:111], v[152:155], v[196:199], v[108:111]
	v_mfma_f32_16x16x32_bf16 v[100:103], v[160:163], v[196:199], v[100:103]
	v_mfma_f32_16x16x32_bf16 v[92:95], v[152:155], v[204:207], v[92:95]
	v_mfma_f32_16x16x32_bf16 v[84:87], v[160:163], v[204:207], v[84:87]
	v_mfma_f32_16x16x32_bf16 v[76:79], v[152:155], v[212:215], v[76:79]
	v_mfma_f32_16x16x32_bf16 v[68:71], v[160:163], v[212:215], v[68:71]
	v_mfma_f32_16x16x32_bf16 v[124:127], v[164:167], v[180:183], v[124:127]
	v_mfma_f32_16x16x32_bf16 v[120:123], v[172:175], v[180:183], v[120:123]
	v_mfma_f32_16x16x32_bf16 v[104:107], v[164:167], v[192:195], v[104:107]
	v_mfma_f32_16x16x32_bf16 v[96:99], v[172:175], v[192:195], v[96:99]
	v_mfma_f32_16x16x32_bf16 v[88:91], v[164:167], v[200:203], v[88:91]
	v_mfma_f32_16x16x32_bf16 v[80:83], v[172:175], v[200:203], v[80:83]
	v_mfma_f32_16x16x32_bf16 v[72:75], v[164:167], v[208:211], v[72:75]
	v_mfma_f32_16x16x32_bf16 v[64:67], v[172:175], v[208:211], v[64:67]
	v_mfma_f32_16x16x32_bf16 v[124:127], v[168:171], v[184:187], v[124:127]
	v_mfma_f32_16x16x32_bf16 v[120:123], v[176:179], v[184:187], v[120:123]
	v_mfma_f32_16x16x32_bf16 v[104:107], v[168:171], v[196:199], v[104:107]
	v_mfma_f32_16x16x32_bf16 v[96:99], v[176:179], v[196:199], v[96:99]
	v_mfma_f32_16x16x32_bf16 v[88:91], v[168:171], v[204:207], v[88:91]
	v_mfma_f32_16x16x32_bf16 v[80:83], v[176:179], v[204:207], v[80:83]
	v_mfma_f32_16x16x32_bf16 v[72:75], v[168:171], v[212:215], v[72:75]
	v_mfma_f32_16x16x32_bf16 v[64:67], v[176:179], v[212:215], v[64:67]
	s_barrier
	v_lshl_add_u64 v[216:217], s[84:85], 0, v[190:191]
	s_add_i32 s84, s74, s14
	s_mov_b32 m0, s84
	ds_read_b128 v[180:183], v143 offset:16384
	ds_read_b128 v[184:187], v143 offset:17408
	ds_read_b128 v[192:195], v143 offset:18432
	ds_read_b128 v[196:199], v143 offset:19456
	ds_read_b128 v[200:203], v143 offset:20480
	ds_read_b128 v[204:207], v143 offset:21504
	ds_read_b128 v[208:211], v143 offset:22528
	ds_read_b128 v[212:215], v143 offset:23552
	global_load_lds_dwordx4 v[216:217], off
	v_lshl_add_u64 v[220:221], v[216:217], 0, s[6:7]
	s_add_i32 m0, s84, 0x2000
	s_add_i32 s84, s75, s14
	global_load_lds_dwordx4 v[220:221], off
	v_lshl_add_u64 v[220:221], v[216:217], 0, s[8:9]
	s_mov_b32 m0, s84
	s_nop 0
	global_load_lds_dwordx4 v[220:221], off
	v_lshl_add_u64 v[220:221], v[216:217], 0, s[10:11]
	s_add_i32 m0, s84, 0x2000
	s_nop 0
	global_load_lds_dwordx4 v[220:221], off
	v_lshl_add_u64 v[220:221], s[78:79], 0, v[190:191]
	s_mov_b32 m0, s18
	v_lshl_add_u64 v[222:223], v[220:221], 0, s[6:7]
	global_load_lds_dwordx4 v[220:221], off
	s_mov_b32 m0, s19
	s_nop 0
	global_load_lds_dwordx4 v[222:223], off
	s_waitcnt vmcnt(8)
	s_waitcnt lgkmcnt(0)
	s_barrier
; #define PG8_STAGE(bufoff, gbase, voff) do { _Pragma("unroll") for (int _i = 0; _i < 2; ++_i) \
;         __builtin_amdgcn_global_load_lds((const unsigned*)((const char*)(gbase) + (voff)[_i]), (PG8_LAS unsigned*)(lds + (bufoff) + ldsw + _i * 8192), 16, 0, 0); } while (0)
; #define PG8_LDA(dst, b, h) do { _Pragma("unroll") for (int m = 0; m < 4; ++m) _Pragma("unroll") for (int k = 0; k < 2; ++k) dst[m][k] = *(const PG8_LAS bf16x8*)(lds + PG8_SA(b, h) + aoff + m * 2048 + k * 1024); } while (0)
; #define PG8_LDB(dst, b, h) do { _Pragma("unroll") for (int n = 0; n < 2; ++n) _Pragma("unroll") for (int k = 0; k < 2; ++k) dst[n][k] = *(const PG8_LAS bf16x8*)(lds + PG8_SB(b, h) + boff + n * 2048 + k * 1024); } while (0)
; #define PG8_MMA(ai, bj, At, Bt) do { __builtin_amdgcn_s_setprio(1); _Pragma("unroll") for (int m = 0; m < 4; ++m) _Pragma("unroll") for (int n = 0; n < 2; ++n) _Pragma("unroll") for (int k = 0; k < 2; ++k) \
;         acc[ai][bj][m][n] = __builtin_amdgcn_mfma_f32_16x16x32_bf16(Bt[n][k], At[m][k], acc[ai][bj][m][n], 0, 0, 0); __builtin_amdgcn_s_setprio(0); } while (0)
; #define PG8_WAIT_V(n) asm volatile("s_waitcnt vmcnt(" #n ")" ::: "memory")
; #define PG8_WAIT_L(n) asm volatile("s_waitcnt lgkmcnt(" #n ")" ::: "memory")
; #define PG8_BAR __builtin_amdgcn_s_barrier()
; #define PG8_SCHED __builtin_amdgcn_sched_barrier(0)
; template <class Epi, class Sched, bool ALIGN_EPI = false, bool SP2 = false>
; __device__ __forceinline__ void gemm_phase(PG8_LAS unsigned char* lds, const Gemm g, const Sched& S, const Epi& E) {
;     ...
;             PG8_WAIT_V(8); PG8_WAIT_L(0); PG8_BAR; PG8_MMA(1, 0, At, B0); PG8_MMA(1, 1, At, B1); PG8_BAR; PG8_SCHED;
;             PG8_LDB(B0, 1, 0); PG8_LDB(B1, 1, 1); PG8_SCHED; PG8_LDA(At, 1, 0); PG8_STAGE(PG8_SA(0, 1), a2 + hstepA, voffA);
;             PG8_WAIT_V(8); PG8_WAIT_L(0); PG8_BAR; PG8_MMA(0, 0, At, B0); PG8_MMA(0, 1, At, B1); PG8_BAR; PG8_SCHED;
	s_waitcnt lgkmcnt(0)
	v_mfma_f32_16x16x32_bf16 v[60:63], v[148:151], v[180:183], v[60:63]
	v_mfma_f32_16x16x32_bf16 v[52:55], v[156:159], v[180:183], v[52:55]
	v_mfma_f32_16x16x32_bf16 v[44:47], v[148:151], v[192:195], v[44:47]
	v_mfma_f32_16x16x32_bf16 v[36:39], v[156:159], v[192:195], v[36:39]
	v_mfma_f32_16x16x32_bf16 v[28:31], v[148:151], v[200:203], v[28:31]
	v_mfma_f32_16x16x32_bf16 v[20:23], v[156:159], v[200:203], v[20:23]
	v_mfma_f32_16x16x32_bf16 v[12:15], v[148:151], v[208:211], v[12:15]
	v_mfma_f32_16x16x32_bf16 v[4:7], v[156:159], v[208:211], v[4:7]
	v_mfma_f32_16x16x32_bf16 v[60:63], v[152:155], v[184:187], v[60:63]
	v_mfma_f32_16x16x32_bf16 v[52:55], v[160:163], v[184:187], v[52:55]
	v_mfma_f32_16x16x32_bf16 v[44:47], v[152:155], v[196:199], v[44:47]
	v_mfma_f32_16x16x32_bf16 v[36:39], v[160:163], v[196:199], v[36:39]
	v_mfma_f32_16x16x32_bf16 v[28:31], v[152:155], v[204:207], v[28:31]
	v_mfma_f32_16x16x32_bf16 v[20:23], v[160:163], v[204:207], v[20:23]
	v_mfma_f32_16x16x32_bf16 v[12:15], v[152:155], v[212:215], v[12:15]
	v_mfma_f32_16x16x32_bf16 v[4:7], v[160:163], v[212:215], v[4:7]
	v_mfma_f32_16x16x32_bf16 v[56:59], v[164:167], v[180:183], v[56:59]
	v_mfma_f32_16x16x32_bf16 v[48:51], v[172:175], v[180:183], v[48:51]
	v_mfma_f32_16x16x32_bf16 v[40:43], v[164:167], v[192:195], v[40:43]
	v_mfma_f32_16x16x32_bf16 v[32:35], v[172:175], v[192:195], v[32:35]
	v_mfma_f32_16x16x32_bf16 v[24:27], v[164:167], v[200:203], v[24:27]
	v_mfma_f32_16x16x32_bf16 v[16:19], v[172:175], v[200:203], v[16:19]
	v_mfma_f32_16x16x32_bf16 v[8:11], v[164:167], v[208:211], v[8:11]
	v_mfma_f32_16x16x32_bf16 v[0:3], v[172:175], v[208:211], v[0:3]
	v_mfma_f32_16x16x32_bf16 v[56:59], v[168:171], v[184:187], v[56:59]
	v_mfma_f32_16x16x32_bf16 v[48:51], v[176:179], v[184:187], v[48:51]
	v_mfma_f32_16x16x32_bf16 v[40:43], v[168:171], v[196:199], v[40:43]
	v_mfma_f32_16x16x32_bf16 v[32:35], v[176:179], v[196:199], v[32:35]
	v_mfma_f32_16x16x32_bf16 v[24:27], v[168:171], v[204:207], v[24:27]
	v_mfma_f32_16x16x32_bf16 v[16:19], v[176:179], v[204:207], v[16:19]
	v_mfma_f32_16x16x32_bf16 v[8:11], v[168:171], v[212:215], v[8:11]
	v_mfma_f32_16x16x32_bf16 v[0:3], v[176:179], v[212:215], v[0:3]
	s_barrier
	ds_read_b128 v[148:151], v144
	ds_read_b128 v[152:155], v144 offset:1024
	ds_read_b128 v[156:159], v144 offset:2048
	ds_read_b128 v[160:163], v144 offset:3072
	ds_read_b128 v[164:167], v145
	ds_read_b128 v[168:171], v145 offset:1024
	ds_read_b128 v[172:175], v145 offset:2048
	ds_read_b128 v[176:179], v145 offset:3072
	s_mov_b32 m0, s66
	v_lshl_add_u64 v[222:223], v[220:221], 0, s[8:9]
	ds_read_b128 v[180:183], v143 offset:32768
	ds_read_b128 v[184:187], v143 offset:33792
	ds_read_b128 v[192:195], v143 offset:34816
	ds_read_b128 v[196:199], v143 offset:35840
	ds_read_b128 v[200:203], v143 offset:36864
	ds_read_b128 v[204:207], v143 offset:37888
	ds_read_b128 v[208:211], v143 offset:38912
	ds_read_b128 v[212:215], v143 offset:39936
	global_load_lds_dwordx4 v[222:223], off
	v_lshl_add_u64 v[222:223], v[220:221], 0, s[10:11]
	s_mov_b32 m0, s67
	s_nop 0
	global_load_lds_dwordx4 v[222:223], off
	s_waitcnt vmcnt(8)
	s_waitcnt lgkmcnt(0)
	s_barrier
	s_waitcnt lgkmcnt(0)
	v_mfma_f32_16x16x32_bf16 v[116:119], v[148:151], v[180:183], v[116:119]
	v_mfma_f32_16x16x32_bf16 v[112:115], v[156:159], v[180:183], v[112:115]
	v_mfma_f32_16x16x32_bf16 v[108:111], v[148:151], v[192:195], v[108:111]
	v_mfma_f32_16x16x32_bf16 v[100:103], v[156:159], v[192:195], v[100:103]
	v_mfma_f32_16x16x32_bf16 v[92:95], v[148:151], v[200:203], v[92:95]
	v_mfma_f32_16x16x32_bf16 v[84:87], v[156:159], v[200:203], v[84:87]
	v_mfma_f32_16x16x32_bf16 v[76:79], v[148:151], v[208:211], v[76:79]
	v_mfma_f32_16x16x32_bf16 v[68:71], v[156:159], v[208:211], v[68:71]
	v_mfma_f32_16x16x32_bf16 v[116:119], v[152:155], v[184:187], v[116:119]
	v_mfma_f32_16x16x32_bf16 v[112:115], v[160:163], v[184:187], v[112:115]
	v_mfma_f32_16x16x32_bf16 v[108:111], v[152:155], v[196:199], v[108:111]
	v_mfma_f32_16x16x32_bf16 v[100:103], v[160:163], v[196:199], v[100:103]
	v_mfma_f32_16x16x32_bf16 v[92:95], v[152:155], v[204:207], v[92:95]
	v_mfma_f32_16x16x32_bf16 v[84:87], v[160:163], v[204:207], v[84:87]
	v_mfma_f32_16x16x32_bf16 v[76:79], v[152:155], v[212:215], v[76:79]
	v_mfma_f32_16x16x32_bf16 v[68:71], v[160:163], v[212:215], v[68:71]
	v_mfma_f32_16x16x32_bf16 v[124:127], v[164:167], v[180:183], v[124:127]
	v_mfma_f32_16x16x32_bf16 v[120:123], v[172:175], v[180:183], v[120:123]
	v_mfma_f32_16x16x32_bf16 v[104:107], v[164:167], v[192:195], v[104:107]
	v_mfma_f32_16x16x32_bf16 v[96:99], v[172:175], v[192:195], v[96:99]
	v_mfma_f32_16x16x32_bf16 v[88:91], v[164:167], v[200:203], v[88:91]
	v_mfma_f32_16x16x32_bf16 v[80:83], v[172:175], v[200:203], v[80:83]
	v_mfma_f32_16x16x32_bf16 v[72:75], v[164:167], v[208:211], v[72:75]
	v_mfma_f32_16x16x32_bf16 v[64:67], v[172:175], v[208:211], v[64:67]
	v_mfma_f32_16x16x32_bf16 v[124:127], v[168:171], v[184:187], v[124:127]
	v_mfma_f32_16x16x32_bf16 v[120:123], v[176:179], v[184:187], v[120:123]
	v_mfma_f32_16x16x32_bf16 v[104:107], v[168:171], v[196:199], v[104:107]
	v_mfma_f32_16x16x32_bf16 v[96:99], v[176:179], v[196:199], v[96:99]
	v_mfma_f32_16x16x32_bf16 v[88:91], v[168:171], v[204:207], v[88:91]
	v_mfma_f32_16x16x32_bf16 v[80:83], v[176:179], v[204:207], v[80:83]
	v_mfma_f32_16x16x32_bf16 v[72:75], v[168:171], v[212:215], v[72:75]
	v_mfma_f32_16x16x32_bf16 v[64:67], v[176:179], v[212:215], v[64:67]
	s_barrier
; #define PG8_STAGE(bufoff, gbase, voff) do { _Pragma("unroll") for (int _i = 0; _i < 2; ++_i) \
;         __builtin_amdgcn_global_load_lds((const unsigned*)((const char*)(gbase) + (voff)[_i]), (PG8_LAS unsigned*)(lds + (bufoff) + ldsw + _i * 8192), 16, 0, 0); } while (0)
; #define PG8_LDA(dst, b, h) do { _Pragma("unroll") for (int m = 0; m < 4; ++m) _Pragma("unroll") for (int k = 0; k < 2; ++k) dst[m][k] = *(const PG8_LAS bf16x8*)(lds + PG8_SA(b, h) + aoff + m * 2048 + k * 1024); } while (0)
; #define PG8_MMA(ai, bj, At, Bt) do { __builtin_amdgcn_s_setprio(1); _Pragma("unroll") for (int m = 0; m < 4; ++m) _Pragma("unroll") for (int n = 0; n < 2; ++n) _Pragma("unroll") for (int k = 0; k < 2; ++k) \
;         acc[ai][bj][m][n] = __builtin_amdgcn_mfma_f32_16x16x32_bf16(Bt[n][k], At[m][k], acc[ai][bj][m][n], 0, 0, 0); __builtin_amdgcn_s_setprio(0); } while (0)
; #define PG8_WAIT_V(n) asm volatile("s_waitcnt vmcnt(" #n ")" ::: "memory")
; #define PG8_WAIT_L(n) asm volatile("s_waitcnt lgkmcnt(" #n ")" ::: "memory")
; #define PG8_BAR __builtin_amdgcn_s_barrier()
; #define PG8_SCHED __builtin_amdgcn_sched_barrier(0)
; template <class Epi, class Sched, bool ALIGN_EPI = false, bool SP2 = false>
; __device__ __forceinline__ void gemm_phase(PG8_LAS unsigned char* lds, const Gemm g, const Sched& S, const Epi& E) {
;     ...
;             PG8_LDA(At, 1, 1); PG8_STAGE(PG8_SB(1, 0), b3, voffB); PG8_STAGE(PG8_SB(1, 1), b3 + hstepB, voffB); PG8_STAGE(PG8_SA(1, 0), a3, voffA);
;             PG8_WAIT_V(8); PG8_WAIT_L(0); PG8_BAR; PG8_MMA(1, 0, At, B0); PG8_MMA(1, 1, At, B1); PG8_BAR; PG8_SCHED;
	s_add_i32 s78, s76, s14
	v_lshl_add_u64 v[222:223], v[216:217], 0, s[34:35]
	s_mov_b32 m0, s78
	ds_read_b128 v[180:183], v143 offset:49152
	ds_read_b128 v[184:187], v143 offset:50176
	ds_read_b128 v[192:195], v143 offset:51200
	ds_read_b128 v[196:199], v143 offset:52224
	ds_read_b128 v[200:203], v143 offset:53248
	ds_read_b128 v[204:207], v143 offset:54272
	ds_read_b128 v[208:211], v143 offset:55296
	ds_read_b128 v[212:215], v143 offset:56320
	global_load_lds_dwordx4 v[222:223], off
	v_lshl_add_u64 v[222:223], v[216:217], 0, s[36:37]
	s_add_i32 m0, s78, 0x2000
	s_add_i32 s78, s77, s14
	global_load_lds_dwordx4 v[222:223], off
	v_lshl_add_u64 v[222:223], v[216:217], 0, s[38:39]
	s_mov_b32 m0, s78
	v_lshl_add_u64 v[216:217], v[216:217], 0, s[40:41]
	global_load_lds_dwordx4 v[222:223], off
	s_add_i32 m0, s78, 0x2000
	s_nop 0
	global_load_lds_dwordx4 v[216:217], off
	v_lshl_add_u64 v[216:217], v[220:221], 0, s[34:35]
	s_mov_b32 m0, s68
	s_nop 0
	global_load_lds_dwordx4 v[216:217], off
	v_lshl_add_u64 v[216:217], v[220:221], 0, s[36:37]
	s_mov_b32 m0, s69
	s_nop 0
	global_load_lds_dwordx4 v[216:217], off
	s_waitcnt vmcnt(8)
	s_waitcnt lgkmcnt(0)
	s_barrier
	s_waitcnt lgkmcnt(0)
	v_mfma_f32_16x16x32_bf16 v[60:63], v[148:151], v[180:183], v[60:63]
	v_mfma_f32_16x16x32_bf16 v[52:55], v[156:159], v[180:183], v[52:55]
	v_mfma_f32_16x16x32_bf16 v[44:47], v[148:151], v[192:195], v[44:47]
	v_mfma_f32_16x16x32_bf16 v[36:39], v[156:159], v[192:195], v[36:39]
	v_mfma_f32_16x16x32_bf16 v[28:31], v[148:151], v[200:203], v[28:31]
	v_mfma_f32_16x16x32_bf16 v[20:23], v[156:159], v[200:203], v[20:23]
	v_mfma_f32_16x16x32_bf16 v[12:15], v[148:151], v[208:211], v[12:15]
	v_mfma_f32_16x16x32_bf16 v[4:7], v[156:159], v[208:211], v[4:7]
	v_mfma_f32_16x16x32_bf16 v[60:63], v[152:155], v[184:187], v[60:63]
	v_mfma_f32_16x16x32_bf16 v[52:55], v[160:163], v[184:187], v[52:55]
	v_mfma_f32_16x16x32_bf16 v[44:47], v[152:155], v[196:199], v[44:47]
	v_mfma_f32_16x16x32_bf16 v[36:39], v[160:163], v[196:199], v[36:39]
	v_mfma_f32_16x16x32_bf16 v[28:31], v[152:155], v[204:207], v[28:31]
	v_mfma_f32_16x16x32_bf16 v[20:23], v[160:163], v[204:207], v[20:23]
	v_mfma_f32_16x16x32_bf16 v[12:15], v[152:155], v[212:215], v[12:15]
	v_mfma_f32_16x16x32_bf16 v[4:7], v[160:163], v[212:215], v[4:7]
	v_mfma_f32_16x16x32_bf16 v[56:59], v[164:167], v[180:183], v[56:59]
	v_mfma_f32_16x16x32_bf16 v[48:51], v[172:175], v[180:183], v[48:51]
	v_mfma_f32_16x16x32_bf16 v[40:43], v[164:167], v[192:195], v[40:43]
	v_mfma_f32_16x16x32_bf16 v[32:35], v[172:175], v[192:195], v[32:35]
	v_mfma_f32_16x16x32_bf16 v[24:27], v[164:167], v[200:203], v[24:27]
	v_mfma_f32_16x16x32_bf16 v[16:19], v[172:175], v[200:203], v[16:19]
	v_mfma_f32_16x16x32_bf16 v[8:11], v[164:167], v[208:211], v[8:11]
	v_mfma_f32_16x16x32_bf16 v[0:3], v[172:175], v[208:211], v[0:3]
	v_mfma_f32_16x16x32_bf16 v[56:59], v[168:171], v[184:187], v[56:59]
	v_mfma_f32_16x16x32_bf16 v[48:51], v[176:179], v[184:187], v[48:51]
	v_mfma_f32_16x16x32_bf16 v[40:43], v[168:171], v[196:199], v[40:43]
	v_mfma_f32_16x16x32_bf16 v[32:35], v[176:179], v[196:199], v[32:35]
	v_mfma_f32_16x16x32_bf16 v[24:27], v[168:171], v[204:207], v[24:27]
	v_mfma_f32_16x16x32_bf16 v[16:19], v[176:179], v[204:207], v[16:19]
	v_mfma_f32_16x16x32_bf16 v[8:11], v[168:171], v[212:215], v[8:11]
	v_mfma_f32_16x16x32_bf16 v[0:3], v[176:179], v[212:215], v[0:3]
	s_barrier
	s_add_i32 s82, s82, 2
	s_add_u32 s62, s62, 0x10000
	s_addc_u32 s63, s63, 0
	s_add_u32 s64, s64, 0x10000
	s_addc_u32 s65, s65, 0
	s_cmp_gt_u32 s82, 13
	s_cbranch_scc0 .LBB0_838
